# attention score loops (A-layer mixer): K fragments of 3 key tiles read as a batch into spare VGPRs, double buffered, 3+3 independent MFMAs per batch
# speedup vs baseline: 1.0065x; 1.0065x over previous
.LBB0_151:
	s_or_b64 exec, exec, s[10:11]
	v_and_b32_e32 v5, 64, v229
	v_mov_b32_e32 v1, v4
	v_xor_b32_e32 v4, 16, v229
	v_add_u32_e32 v5, 64, v5
	v_cmp_lt_i32_e32 vcc, v4, v5
	v_and_b32_e32 v71, 15, v52
	v_mad_u32_u24 v79, v71, s13, v72
	v_cndmask_b32_e32 v78, v229, v4, vcc
	v_xor_b32_e32 v4, 32, v229
	v_cmp_lt_i32_e32 vcc, v4, v5
	v_mov_b32_e32 v65, v6
	v_cndmask_b32_e32 v73, v229, v4, vcc
	v_lshlrev_b32_e32 v73, 2, v73
	ds_read_b128 v[116:119], v79
	ds_read_b128 v[120:123], v79 offset:64
	ds_read_b128 v[124:127], v79 offset:2304
	ds_read_b128 v[128:131], v79 offset:2368
	ds_read_b128 v[132:135], v79 offset:4608
	ds_read_b128 v[136:139], v79 offset:4672
	ds_read_b128 v[140:143], v79 offset:6912
	ds_read_b128 v[144:147], v79 offset:6976
	ds_read_b128 v[148:151], v79 offset:9216
	ds_read_b128 v[152:155], v79 offset:9280
	ds_read_b128 v[156:159], v79 offset:11520
	ds_read_b128 v[160:163], v79 offset:11584
	s_waitcnt lgkmcnt(6)
	v_mfma_f32_16x16x32_bf16 v[60:63], v[116:119], v[0:3], 0
	v_mfma_f32_16x16x32_bf16 v[56:59], v[124:127], v[0:3], 0
	v_mfma_f32_16x16x32_bf16 v[52:55], v[132:135], v[0:3], 0
	v_mfma_f32_16x16x32_bf16 v[60:63], v[120:123], v[64:67], v[60:63]
	v_mfma_f32_16x16x32_bf16 v[56:59], v[128:131], v[64:67], v[56:59]
	v_mfma_f32_16x16x32_bf16 v[52:55], v[136:139], v[64:67], v[52:55]
	ds_read_b128 v[116:119], v79 offset:13824
	ds_read_b128 v[120:123], v79 offset:13888
	ds_read_b128 v[124:127], v79 offset:16128
	ds_read_b128 v[128:131], v79 offset:16192
	ds_read_b128 v[132:135], v79 offset:18432
	ds_read_b128 v[136:139], v79 offset:18496
	s_waitcnt lgkmcnt(6)
	v_mfma_f32_16x16x32_bf16 v[48:51], v[140:143], v[0:3], 0
	v_mfma_f32_16x16x32_bf16 v[44:47], v[148:151], v[0:3], 0
	v_mfma_f32_16x16x32_bf16 v[40:43], v[156:159], v[0:3], 0
	v_mfma_f32_16x16x32_bf16 v[48:51], v[144:147], v[64:67], v[48:51]
	v_mfma_f32_16x16x32_bf16 v[44:47], v[152:155], v[64:67], v[44:47]
	v_mfma_f32_16x16x32_bf16 v[40:43], v[160:163], v[64:67], v[40:43]
	ds_read_b128 v[140:143], v79 offset:20736
	ds_read_b128 v[144:147], v79 offset:20800
	ds_read_b128 v[148:151], v79 offset:23040
	ds_read_b128 v[152:155], v79 offset:23104
	ds_read_b128 v[156:159], v79 offset:25344
	ds_read_b128 v[160:163], v79 offset:25408
	s_waitcnt lgkmcnt(6)
	v_mfma_f32_16x16x32_bf16 v[36:39], v[116:119], v[0:3], 0
	v_mfma_f32_16x16x32_bf16 v[32:35], v[124:127], v[0:3], 0
	v_mfma_f32_16x16x32_bf16 v[28:31], v[132:135], v[0:3], 0
	v_mfma_f32_16x16x32_bf16 v[36:39], v[120:123], v[64:67], v[36:39]
	v_mfma_f32_16x16x32_bf16 v[32:35], v[128:131], v[64:67], v[32:35]
	v_mfma_f32_16x16x32_bf16 v[28:31], v[136:139], v[64:67], v[28:31]
	ds_read_b128 v[116:119], v79 offset:27648
	ds_read_b128 v[120:123], v79 offset:27712
	ds_read_b128 v[124:127], v79 offset:29952
	ds_read_b128 v[128:131], v79 offset:30016
	ds_read_b128 v[132:135], v79 offset:32256
	ds_read_b128 v[136:139], v79 offset:32320
	s_waitcnt lgkmcnt(6)
	v_mfma_f32_16x16x32_bf16 v[24:27], v[140:143], v[0:3], 0
	v_mfma_f32_16x16x32_bf16 v[20:23], v[148:151], v[0:3], 0
	v_mfma_f32_16x16x32_bf16 v[16:19], v[156:159], v[0:3], 0
	v_mfma_f32_16x16x32_bf16 v[24:27], v[144:147], v[64:67], v[24:27]
	v_mfma_f32_16x16x32_bf16 v[20:23], v[152:155], v[64:67], v[20:23]
	v_mfma_f32_16x16x32_bf16 v[16:19], v[160:163], v[64:67], v[16:19]
	s_waitcnt lgkmcnt(0)
	v_mfma_f32_16x16x32_bf16 v[12:15], v[116:119], v[0:3], 0
	v_mfma_f32_16x16x32_bf16 v[8:11], v[124:127], v[0:3], 0
	v_mfma_f32_16x16x32_bf16 v[4:7], v[132:135], v[0:3], 0
	v_mfma_f32_16x16x32_bf16 v[12:15], v[120:123], v[64:67], v[12:15]
	v_mfma_f32_16x16x32_bf16 v[8:11], v[128:131], v[64:67], v[8:11]
	v_mfma_f32_16x16x32_bf16 v[4:7], v[136:139], v[64:67], v[4:7]
	ds_read_b128 v[116:119], v79 offset:34560
	ds_read_b128 v[120:123], v79 offset:34624
	s_waitcnt lgkmcnt(0)
	v_mfma_f32_16x16x32_bf16 v[124:127], v[116:119], v[0:3], 0
	v_mfma_f32_16x16x32_bf16 v[0:3], v[120:123], v[64:67], v[124:127]
	v_mul_f32_e32 v64, 0x3e000000, v60
	v_mul_f32_e32 v65, 0x3e000000, v61
	s_mov_b32 s2, 0xff61b1e6
	v_max3_f32 v64, v64, s2, v65
	v_mul_f32_e32 v65, 0x3e000000, v62
	v_mul_f32_e32 v66, 0x3e000000, v63
	v_max3_f32 v64, v64, v65, v66
	v_mul_f32_e32 v65, 0x3e000000, v56
	v_mul_f32_e32 v66, 0x3e000000, v57
	v_max3_f32 v64, v64, v65, v66
	v_mul_f32_e32 v65, 0x3e000000, v58
	v_mul_f32_e32 v66, 0x3e000000, v59
	v_max3_f32 v64, v64, v65, v66
	v_mul_f32_e32 v65, 0x3e000000, v52
	v_mul_f32_e32 v66, 0x3e000000, v53
	v_max3_f32 v64, v64, v65, v66
	v_mul_f32_e32 v65, 0x3e000000, v54
	v_mul_f32_e32 v66, 0x3e000000, v55
	v_max3_f32 v64, v64, v65, v66
	v_mul_f32_e32 v65, 0x3e000000, v48
	v_mul_f32_e32 v66, 0x3e000000, v49
	v_max3_f32 v64, v64, v65, v66
	v_mul_f32_e32 v65, 0x3e000000, v50
	v_mul_f32_e32 v66, 0x3e000000, v51
	v_max3_f32 v64, v64, v65, v66
	v_mul_f32_e32 v65, 0x3e000000, v44
	v_mul_f32_e32 v66, 0x3e000000, v45
	v_max3_f32 v64, v64, v65, v66
	v_mul_f32_e32 v65, 0x3e000000, v46
	v_mul_f32_e32 v66, 0x3e000000, v47
	v_max3_f32 v64, v64, v65, v66
	v_mul_f32_e32 v65, 0x3e000000, v40
	v_mul_f32_e32 v66, 0x3e000000, v41
	v_max3_f32 v64, v64, v65, v66
	v_mul_f32_e32 v65, 0x3e000000, v42
	v_mul_f32_e32 v66, 0x3e000000, v43
	v_max3_f32 v64, v64, v65, v66
	v_mul_f32_e32 v65, 0x3e000000, v36
	v_mul_f32_e32 v66, 0x3e000000, v37
	v_max3_f32 v64, v64, v65, v66
	v_mul_f32_e32 v65, 0x3e000000, v38
	v_mul_f32_e32 v66, 0x3e000000, v39
	v_max3_f32 v64, v64, v65, v66
	v_mul_f32_e32 v65, 0x3e000000, v32
	v_mul_f32_e32 v66, 0x3e000000, v33
	v_max3_f32 v64, v64, v65, v66
	v_mul_f32_e32 v65, 0x3e000000, v34
	v_mul_f32_e32 v66, 0x3e000000, v35
	v_max3_f32 v64, v64, v65, v66
	v_mul_f32_e32 v65, 0x3e000000, v28
	v_mul_f32_e32 v66, 0x3e000000, v29
	v_max3_f32 v64, v64, v65, v66
	v_mul_f32_e32 v65, 0x3e000000, v30
	v_mul_f32_e32 v66, 0x3e000000, v31
	v_max3_f32 v64, v64, v65, v66
	v_mul_f32_e32 v65, 0x3e000000, v24
	v_mul_f32_e32 v66, 0x3e000000, v25
	v_max3_f32 v64, v64, v65, v66
	v_mul_f32_e32 v65, 0x3e000000, v26
	v_mul_f32_e32 v66, 0x3e000000, v27
	v_max3_f32 v64, v64, v65, v66
	v_mul_f32_e32 v65, 0x3e000000, v20
	v_mul_f32_e32 v66, 0x3e000000, v21
	v_max3_f32 v64, v64, v65, v66
	v_mul_f32_e32 v65, 0x3e000000, v22
	v_mul_f32_e32 v66, 0x3e000000, v23
	v_max3_f32 v64, v64, v65, v66
	v_mul_f32_e32 v65, 0x3e000000, v16
	v_mul_f32_e32 v66, 0x3e000000, v17
	v_max3_f32 v64, v64, v65, v66
	v_mul_f32_e32 v65, 0x3e000000, v18
	v_mul_f32_e32 v66, 0x3e000000, v19
	v_max3_f32 v64, v64, v65, v66
	v_mul_f32_e32 v65, 0x3e000000, v12
	v_mul_f32_e32 v66, 0x3e000000, v13
	v_max3_f32 v64, v64, v65, v66
	v_mul_f32_e32 v65, 0x3e000000, v14
	v_mul_f32_e32 v66, 0x3e000000, v15
	v_max3_f32 v64, v64, v65, v66
	v_mul_f32_e32 v65, 0x3e000000, v8
	v_mul_f32_e32 v66, 0x3e000000, v9
	v_max3_f32 v64, v64, v65, v66
	v_mul_f32_e32 v65, 0x3e000000, v10
	v_mul_f32_e32 v66, 0x3e000000, v11
	v_max3_f32 v64, v64, v65, v66
	v_mul_f32_e32 v65, 0x3e000000, v4
	v_mul_f32_e32 v66, 0x3e000000, v5
	v_max3_f32 v64, v64, v65, v66
	v_mul_f32_e32 v65, 0x3e000000, v6
	v_mul_f32_e32 v66, 0x3e000000, v7
	v_max3_f32 v64, v64, v65, v66
	v_mul_f32_e32 v65, 0x3e000000, v0
	v_mul_f32_e32 v66, 0x3e000000, v1
	v_max3_f32 v64, v64, v65, v66
	v_mul_f32_e32 v65, 0x3e000000, v2
	v_mul_f32_e32 v66, 0x3e000000, v3
	v_max3_f32 v64, v64, v65, v66
	v_lshlrev_b32_e32 v74, 2, v78
	ds_bpermute_b32 v65, v74, v64
	s_mov_b32 s2, 0x3e000000
	v_sub_u32_e32 v72, v72, v70
	s_waitcnt lgkmcnt(0)
	v_max_f32_e32 v65, v65, v65
	v_max_f32_e32 v64, v64, v65
	ds_bpermute_b32 v65, v73, v64
	s_waitcnt lgkmcnt(0)
	v_max_f32_e32 v65, v65, v65
	v_max_f32_e32 v75, v64, v65
	v_fma_f32 v60, v60, s2, -v75
	v_fma_f32 v61, v61, s2, -v75
	v_mul_f32_e32 v60, 0x3fb8aa3b, v60
	v_mul_f32_e32 v61, 0x3fb8aa3b, v61
	v_exp_f32_e32 v60, v60
	v_exp_f32_e32 v64, v61
	v_fma_f32 v61, v62, s2, -v75
	v_mul_f32_e32 v61, 0x3fb8aa3b, v61
	v_exp_f32_e32 v61, v61
	v_add_f32_e32 v65, 0, v60
	v_fma_f32 v63, v63, s2, -v75
	v_add_f32_e32 v65, v64, v65
	v_mul_f32_e32 v63, 0x3fb8aa3b, v63
	v_add_f32_e32 v62, v61, v65
	v_exp_f32_e32 v65, v63
	v_fma_f32 v56, v56, s2, -v75
	v_mul_f32_e32 v56, 0x3fb8aa3b, v56
	v_fma_f32 v57, v57, s2, -v75
	v_add_f32_e32 v63, v65, v62
	v_exp_f32_e32 v62, v56
	v_mul_f32_e32 v57, 0x3fb8aa3b, v57
	v_exp_f32_e32 v66, v57
	v_fma_f32 v57, v58, s2, -v75
	v_mul_f32_e32 v57, 0x3fb8aa3b, v57
	v_add_f32_e32 v56, v62, v63
	v_exp_f32_e32 v63, v57
	v_fma_f32 v57, v59, s2, -v75
	v_mul_f32_e32 v57, 0x3fb8aa3b, v57
	v_fma_f32 v52, v52, s2, -v75
	v_exp_f32_e32 v67, v57
	v_mul_f32_e32 v52, 0x3fb8aa3b, v52
	v_exp_f32_e32 v52, v52
	v_add_f32_e32 v56, v66, v56
	v_add_f32_e32 v56, v63, v56
	v_fma_f32 v53, v53, s2, -v75
	v_add_f32_e32 v56, v67, v56
	v_mul_f32_e32 v53, 0x3fb8aa3b, v53
	v_add_f32_e32 v57, v52, v56
	v_exp_f32_e32 v56, v53
	v_fma_f32 v53, v54, s2, -v75
	v_mul_f32_e32 v53, 0x3fb8aa3b, v53
	v_exp_f32_e32 v53, v53
	v_fma_f32 v55, v55, s2, -v75
	v_add_f32_e32 v57, v56, v57
	v_mul_f32_e32 v55, 0x3fb8aa3b, v55
	v_add_f32_e32 v54, v53, v57
	v_exp_f32_e32 v57, v55
	v_fma_f32 v48, v48, s2, -v75
	v_mul_f32_e32 v48, 0x3fb8aa3b, v48
	v_fma_f32 v49, v49, s2, -v75
	v_add_f32_e32 v55, v57, v54
	v_exp_f32_e32 v54, v48
	v_mul_f32_e32 v49, 0x3fb8aa3b, v49
	v_exp_f32_e32 v58, v49
	v_fma_f32 v49, v50, s2, -v75
	v_mul_f32_e32 v49, 0x3fb8aa3b, v49
	v_add_f32_e32 v48, v54, v55
	v_exp_f32_e32 v55, v49
	v_fma_f32 v49, v51, s2, -v75
	v_mul_f32_e32 v49, 0x3fb8aa3b, v49
	v_fma_f32 v44, v44, s2, -v75
	v_exp_f32_e32 v59, v49
	v_mul_f32_e32 v44, 0x3fb8aa3b, v44
	v_exp_f32_e32 v44, v44
	v_add_f32_e32 v48, v58, v48
	v_add_f32_e32 v48, v55, v48
	v_fma_f32 v45, v45, s2, -v75
	v_add_f32_e32 v48, v59, v48
	v_mul_f32_e32 v45, 0x3fb8aa3b, v45
	v_add_f32_e32 v49, v44, v48
	v_exp_f32_e32 v48, v45
	v_fma_f32 v45, v46, s2, -v75
	v_mul_f32_e32 v45, 0x3fb8aa3b, v45
	v_exp_f32_e32 v45, v45
	v_fma_f32 v47, v47, s2, -v75
	v_add_f32_e32 v49, v48, v49
	v_mul_f32_e32 v47, 0x3fb8aa3b, v47
	v_add_f32_e32 v46, v45, v49
	v_exp_f32_e32 v49, v47
	v_fma_f32 v40, v40, s2, -v75
	v_mul_f32_e32 v40, 0x3fb8aa3b, v40
	v_fma_f32 v41, v41, s2, -v75
	v_add_f32_e32 v47, v49, v46
	v_exp_f32_e32 v46, v40
	v_mul_f32_e32 v41, 0x3fb8aa3b, v41
	v_exp_f32_e32 v50, v41
	v_fma_f32 v41, v42, s2, -v75
	v_mul_f32_e32 v41, 0x3fb8aa3b, v41
	v_add_f32_e32 v40, v46, v47
	v_exp_f32_e32 v47, v41
	v_fma_f32 v41, v43, s2, -v75
	v_mul_f32_e32 v41, 0x3fb8aa3b, v41
	v_fma_f32 v36, v36, s2, -v75
	v_exp_f32_e32 v51, v41
	v_mul_f32_e32 v36, 0x3fb8aa3b, v36
	v_exp_f32_e32 v36, v36
	v_add_f32_e32 v40, v50, v40
	v_add_f32_e32 v40, v47, v40
	v_fma_f32 v37, v37, s2, -v75
	v_add_f32_e32 v40, v51, v40
	v_mul_f32_e32 v37, 0x3fb8aa3b, v37
	v_add_f32_e32 v41, v36, v40
	v_exp_f32_e32 v40, v37
	v_fma_f32 v37, v38, s2, -v75
	v_mul_f32_e32 v37, 0x3fb8aa3b, v37
	v_exp_f32_e32 v37, v37
	v_fma_f32 v39, v39, s2, -v75
	v_add_f32_e32 v41, v40, v41
	v_mul_f32_e32 v39, 0x3fb8aa3b, v39
	v_add_f32_e32 v38, v37, v41
	v_exp_f32_e32 v41, v39
	v_fma_f32 v32, v32, s2, -v75
	v_mul_f32_e32 v32, 0x3fb8aa3b, v32
	v_fma_f32 v33, v33, s2, -v75
	v_add_f32_e32 v39, v41, v38
	v_exp_f32_e32 v38, v32
	v_mul_f32_e32 v33, 0x3fb8aa3b, v33
	v_exp_f32_e32 v42, v33
	v_fma_f32 v33, v34, s2, -v75
	v_mul_f32_e32 v33, 0x3fb8aa3b, v33
	v_add_f32_e32 v32, v38, v39
	v_exp_f32_e32 v39, v33
	v_fma_f32 v33, v35, s2, -v75
	v_mul_f32_e32 v33, 0x3fb8aa3b, v33
	v_fma_f32 v28, v28, s2, -v75
	v_exp_f32_e32 v43, v33
	v_mul_f32_e32 v28, 0x3fb8aa3b, v28
	v_exp_f32_e32 v28, v28
	v_add_f32_e32 v32, v42, v32
	v_add_f32_e32 v32, v39, v32
	v_fma_f32 v29, v29, s2, -v75
	v_add_f32_e32 v32, v43, v32
	v_mul_f32_e32 v29, 0x3fb8aa3b, v29
	v_add_f32_e32 v33, v28, v32
	v_exp_f32_e32 v32, v29
	v_fma_f32 v29, v30, s2, -v75
	v_mul_f32_e32 v29, 0x3fb8aa3b, v29
	v_exp_f32_e32 v29, v29
	v_fma_f32 v31, v31, s2, -v75
	v_add_f32_e32 v33, v32, v33
	v_mul_f32_e32 v31, 0x3fb8aa3b, v31
	v_add_f32_e32 v30, v29, v33
	v_exp_f32_e32 v33, v31
	v_fma_f32 v24, v24, s2, -v75
	v_mul_f32_e32 v24, 0x3fb8aa3b, v24
	v_fma_f32 v25, v25, s2, -v75
	v_add_f32_e32 v31, v33, v30
	v_exp_f32_e32 v30, v24
	v_mul_f32_e32 v25, 0x3fb8aa3b, v25
	v_exp_f32_e32 v34, v25
	v_fma_f32 v25, v26, s2, -v75
	v_mul_f32_e32 v25, 0x3fb8aa3b, v25
	v_add_f32_e32 v24, v30, v31
	v_exp_f32_e32 v31, v25
	v_fma_f32 v25, v27, s2, -v75
	v_mul_f32_e32 v25, 0x3fb8aa3b, v25
	v_fma_f32 v20, v20, s2, -v75
	v_exp_f32_e32 v35, v25
	v_mul_f32_e32 v20, 0x3fb8aa3b, v20
	v_exp_f32_e32 v20, v20
	v_add_f32_e32 v24, v34, v24
	v_add_f32_e32 v24, v31, v24
	v_fma_f32 v21, v21, s2, -v75
	v_add_f32_e32 v24, v35, v24
	v_mul_f32_e32 v21, 0x3fb8aa3b, v21
	v_add_f32_e32 v25, v20, v24
	v_exp_f32_e32 v24, v21
	v_fma_f32 v21, v22, s2, -v75
	v_mul_f32_e32 v21, 0x3fb8aa3b, v21
	v_exp_f32_e32 v21, v21
	v_fma_f32 v23, v23, s2, -v75
	v_add_f32_e32 v25, v24, v25
	v_mul_f32_e32 v23, 0x3fb8aa3b, v23
	v_add_f32_e32 v22, v21, v25
	v_exp_f32_e32 v25, v23
	v_fma_f32 v16, v16, s2, -v75
	v_mul_f32_e32 v16, 0x3fb8aa3b, v16
	v_fma_f32 v17, v17, s2, -v75
	v_add_f32_e32 v23, v25, v22
	v_exp_f32_e32 v22, v16
	v_mul_f32_e32 v17, 0x3fb8aa3b, v17
	v_exp_f32_e32 v26, v17
	v_fma_f32 v17, v18, s2, -v75
	v_mul_f32_e32 v17, 0x3fb8aa3b, v17
	v_add_f32_e32 v16, v22, v23
	v_exp_f32_e32 v23, v17
	v_fma_f32 v17, v19, s2, -v75
	v_mul_f32_e32 v17, 0x3fb8aa3b, v17
	v_fma_f32 v12, v12, s2, -v75
	v_exp_f32_e32 v27, v17
	v_mul_f32_e32 v12, 0x3fb8aa3b, v12
	v_exp_f32_e32 v12, v12
	v_add_f32_e32 v16, v26, v16
	v_add_f32_e32 v16, v23, v16
	v_fma_f32 v13, v13, s2, -v75
	v_add_f32_e32 v16, v27, v16
	v_mul_f32_e32 v13, 0x3fb8aa3b, v13
	v_add_f32_e32 v17, v12, v16
	v_exp_f32_e32 v16, v13
	v_fma_f32 v13, v14, s2, -v75
	v_mul_f32_e32 v13, 0x3fb8aa3b, v13
	v_exp_f32_e32 v13, v13
	v_fma_f32 v15, v15, s2, -v75
	v_add_f32_e32 v17, v16, v17
	v_mul_f32_e32 v15, 0x3fb8aa3b, v15
	v_add_f32_e32 v14, v13, v17
	v_exp_f32_e32 v17, v15
	v_fma_f32 v8, v8, s2, -v75
	v_mul_f32_e32 v8, 0x3fb8aa3b, v8
	v_fma_f32 v9, v9, s2, -v75
	v_add_f32_e32 v15, v17, v14
	v_exp_f32_e32 v14, v8
	v_mul_f32_e32 v9, 0x3fb8aa3b, v9
	v_exp_f32_e32 v18, v9
	v_fma_f32 v9, v10, s2, -v75
	v_mul_f32_e32 v9, 0x3fb8aa3b, v9
	v_add_f32_e32 v8, v14, v15
	v_exp_f32_e32 v15, v9
	v_fma_f32 v9, v11, s2, -v75
	v_mul_f32_e32 v9, 0x3fb8aa3b, v9
	v_fma_f32 v4, v4, s2, -v75
	v_exp_f32_e32 v19, v9
	v_mul_f32_e32 v4, 0x3fb8aa3b, v4
	v_exp_f32_e32 v4, v4
	v_add_f32_e32 v8, v18, v8
	v_add_f32_e32 v8, v15, v8
	v_fma_f32 v5, v5, s2, -v75
	v_add_f32_e32 v8, v19, v8
	v_mul_f32_e32 v5, 0x3fb8aa3b, v5
	v_add_f32_e32 v9, v4, v8
	v_exp_f32_e32 v8, v5
	v_fma_f32 v5, v6, s2, -v75
	v_mul_f32_e32 v5, 0x3fb8aa3b, v5
	v_exp_f32_e32 v5, v5
	v_fma_f32 v7, v7, s2, -v75
	v_add_f32_e32 v9, v8, v9
	v_mul_f32_e32 v7, 0x3fb8aa3b, v7
	v_fma_f32 v0, v0, s2, -v75
	v_add_f32_e32 v6, v5, v9
	v_exp_f32_e32 v9, v7
	v_mul_f32_e32 v0, 0x3fb8aa3b, v0
	v_exp_f32_e32 v0, v0
	v_fma_f32 v1, v1, s2, -v75
	v_add_f32_e32 v6, v9, v6
	v_mul_f32_e32 v1, 0x3fb8aa3b, v1
	v_add_f32_e32 v7, v0, v6
	v_exp_f32_e32 v6, v1
	v_fma_f32 v1, v2, s2, -v75
	v_mul_f32_e32 v1, 0x3fb8aa3b, v1
	v_exp_f32_e32 v1, v1
	v_fma_f32 v3, v3, s2, -v75
	v_add_f32_e32 v7, v6, v7
	v_mul_f32_e32 v3, 0x3fb8aa3b, v3
	v_add_f32_e32 v2, v1, v7
	v_exp_f32_e32 v7, v3
	s_nop 0
	v_add_f32_e32 v2, v7, v2
	ds_bpermute_b32 v3, v74, v2
	s_waitcnt lgkmcnt(0)
	v_add_f32_e32 v2, v2, v3
	ds_bpermute_b32 v3, v73, v2
	s_waitcnt lgkmcnt(0)
	v_add_f32_e32 v2, v2, v3
	v_div_scale_f32 v3, s[2:3], v2, v2, 1.0
	v_rcp_f32_e32 v10, v3
	v_div_scale_f32 v11, vcc, 1.0, v2, 1.0
	s_movk_i32 s2, 0x210
	v_fma_f32 v73, -v3, v10, 1.0
	v_fmac_f32_e32 v10, v73, v10
	v_mul_f32_e32 v73, v11, v10
	v_fma_f32 v74, -v3, v73, v11
	v_fmac_f32_e32 v73, v74, v10
	v_fma_f32 v3, -v3, v73, v11
	v_div_fmas_f32 v3, v3, v10, v73
	v_div_fixup_f32 v2, v3, v2, 1.0
	v_pk_mul_f32 v[10:11], v[60:61], v[2:3] op_sel_hi:[1,0]
	v_pk_mul_f32 v[60:61], v[64:65], v[2:3] op_sel_hi:[1,0]
	v_pk_mul_f32 v[64:65], v[66:67], v[2:3] op_sel_hi:[1,0]
	v_pk_mul_f32 v[62:63], v[62:63], v[2:3] op_sel_hi:[1,0]
	v_bfe_u32 v3, v65, 16, 1
	v_bfe_u32 v66, v64, 16, 1
	v_bfe_u32 v67, v61, 16, 1
	v_bfe_u32 v73, v60, 16, 1
	v_add3_u32 v65, v65, v3, s33
	v_bfe_u32 v3, v10, 16, 1
	v_mad_u32_u24 v71, v71, s2, v72
	v_add3_u32 v73, v60, v73, s33
	v_add3_u32 v74, v61, v67, s33
	v_add3_u32 v64, v64, v66, s33
	v_bfe_u32 v60, v11, 16, 1
	v_bfe_u32 v61, v62, 16, 1
	v_bfe_u32 v66, v63, 16, 1
	v_add3_u32 v10, v10, v3, s33
	v_add_u32_e32 v3, 0x9000, v71
	v_add3_u32 v66, v63, v66, s33
	v_add3_u32 v67, v62, v61, s33
	v_add3_u32 v11, v11, v60, s33
	ds_read2_b64 v[60:63], v3 offset1:4
	v_lshrrev_b32_e32 v10, 16, v10
	v_lshrrev_b32_e32 v11, 16, v11
	v_lshrrev_b32_e32 v72, 16, v67
	v_lshrrev_b32_e32 v66, 16, v66
	v_and_or_b32 v67, v65, s29, v66
	v_and_or_b32 v66, v64, s29, v72
	v_and_or_b32 v65, v74, s29, v11
	v_and_or_b32 v64, v73, s29, v10
	v_add_u32_e32 v10, 0xb000, v71
	s_waitcnt lgkmcnt(0)
	v_mfma_f32_16x16x32_bf16 v[72:75], v[60:63], v[64:67], 0
	ds_read2_b64 v[60:63], v10 offset0:32 offset1:36
	s_waitcnt lgkmcnt(0)
	v_mfma_f32_16x16x32_bf16 v[76:79], v[60:63], v[64:67], 0
	v_add_u32_e32 v60, 0xd000, v71
	v_add_u32_e32 v61, 0xf000, v71
	ds_read2_b64 v[82:85], v60 offset0:64 offset1:68
	ds_read2_b64 v[86:89], v61 offset0:96 offset1:100
	s_waitcnt lgkmcnt(1)
	v_mfma_f32_16x16x32_bf16 v[82:85], v[82:85], v[64:67], 0
	s_waitcnt lgkmcnt(0)
	v_mfma_f32_16x16x32_bf16 v[62:65], v[86:89], v[64:67], 0
	v_mul_f32_e64 v56, v56, v2
	v_mul_f32_e64 v57, v57, v2
	v_pk_mul_f32 v[58:59], v[58:59], v[2:3] op_sel_hi:[1,0]
	v_pk_mul_f32 v[52:53], v[52:53], v[2:3] op_sel_hi:[1,0]
	v_pk_mul_f32 v[54:55], v[54:55], v[2:3] op_sel_hi:[1,0]
	v_bfe_u32 v11, v59, 16, 1
	v_bfe_u32 v66, v58, 16, 1
	v_bfe_u32 v67, v57, 16, 1
	v_bfe_u32 v71, v56, 16, 1
	v_add3_u32 v56, v56, v71, s33
	v_add3_u32 v57, v57, v67, s33
	v_add3_u32 v58, v58, v66, s33
	v_add3_u32 v11, v59, v11, s33
	v_bfe_u32 v59, v52, 16, 1
	v_bfe_u32 v66, v53, 16, 1
	v_bfe_u32 v67, v54, 16, 1
	v_bfe_u32 v71, v55, 16, 1
	v_add3_u32 v71, v55, v71, s33
	v_add3_u32 v67, v54, v67, s33
	v_add3_u32 v66, v53, v66, s33
	v_add3_u32 v59, v52, v59, s33
	ds_read2_b64 v[52:55], v3 offset0:8 offset1:12
	v_lshrrev_b32_e32 v81, 16, v59
	v_lshrrev_b32_e32 v66, 16, v66
	v_lshrrev_b32_e32 v67, 16, v67
	v_lshrrev_b32_e32 v59, 16, v71
	v_and_or_b32 v59, v11, s29, v59
	v_and_or_b32 v58, v58, s29, v67
	v_and_or_b32 v57, v57, s29, v66
	v_and_or_b32 v56, v56, s29, v81
	s_waitcnt lgkmcnt(0)
	s_nop 0
	v_mfma_f32_16x16x32_bf16 v[52:55], v[52:55], v[56:59], v[72:75]
	s_nop 2
	ds_read2_b64 v[72:75], v10 offset0:40 offset1:44
	s_waitcnt lgkmcnt(0)
	v_mfma_f32_16x16x32_bf16 v[72:75], v[72:75], v[56:59], v[76:79]
	s_nop 2
	ds_read2_b64 v[76:79], v60 offset0:72 offset1:76
	s_waitcnt lgkmcnt(0)
	v_mfma_f32_16x16x32_bf16 v[76:79], v[76:79], v[56:59], v[82:85]
	s_nop 2
	ds_read2_b64 v[82:85], v61 offset0:104 offset1:108
	s_waitcnt lgkmcnt(0)
	v_mfma_f32_16x16x32_bf16 v[56:59], v[82:85], v[56:59], v[62:65]
	v_mul_f32_e64 v48, v48, v2
	v_mul_f32_e64 v49, v49, v2
	v_pk_mul_f32 v[50:51], v[50:51], v[2:3] op_sel_hi:[1,0]
	v_pk_mul_f32 v[44:45], v[44:45], v[2:3] op_sel_hi:[1,0]
	v_pk_mul_f32 v[46:47], v[46:47], v[2:3] op_sel_hi:[1,0]
	v_bfe_u32 v11, v51, 16, 1
	v_bfe_u32 v62, v50, 16, 1
	v_bfe_u32 v63, v49, 16, 1
	v_bfe_u32 v64, v48, 16, 1
	v_add3_u32 v48, v48, v64, s33
	v_add3_u32 v49, v49, v63, s33
	v_add3_u32 v50, v50, v62, s33
	v_add3_u32 v11, v51, v11, s33
	v_bfe_u32 v51, v44, 16, 1
	v_bfe_u32 v62, v45, 16, 1
	v_bfe_u32 v63, v46, 16, 1
	v_bfe_u32 v64, v47, 16, 1
	v_add3_u32 v64, v47, v64, s33
	v_add3_u32 v63, v46, v63, s33
	v_add3_u32 v62, v45, v62, s33
	v_add3_u32 v51, v44, v51, s33
	ds_read2_b64 v[44:47], v3 offset0:16 offset1:20
	v_lshrrev_b32_e32 v65, 16, v51
	v_lshrrev_b32_e32 v62, 16, v62
	v_lshrrev_b32_e32 v63, 16, v63
	v_lshrrev_b32_e32 v51, 16, v64
	v_and_or_b32 v51, v11, s29, v51
	v_and_or_b32 v50, v50, s29, v63
	v_and_or_b32 v49, v49, s29, v62
	v_and_or_b32 v48, v48, s29, v65
	ds_read2_b64 v[62:65], v60 offset0:80 offset1:84
	s_waitcnt lgkmcnt(1)
	v_mfma_f32_16x16x32_bf16 v[44:47], v[44:47], v[48:51], v[52:55]
	s_nop 2
	ds_read2_b64 v[52:55], v10 offset0:48 offset1:52
	s_waitcnt lgkmcnt(0)
	v_mfma_f32_16x16x32_bf16 v[52:55], v[52:55], v[48:51], v[72:75]
	s_nop 2
	ds_read2_b64 v[72:75], v61 offset0:112 offset1:116
	v_mfma_f32_16x16x32_bf16 v[62:65], v[62:65], v[48:51], v[76:79]
	s_waitcnt lgkmcnt(0)
	v_mfma_f32_16x16x32_bf16 v[48:51], v[72:75], v[48:51], v[56:59]
	v_mul_f32_e64 v40, v40, v2
	v_mul_f32_e64 v41, v41, v2
	v_pk_mul_f32 v[42:43], v[42:43], v[2:3] op_sel_hi:[1,0]
	v_pk_mul_f32 v[36:37], v[36:37], v[2:3] op_sel_hi:[1,0]
	v_pk_mul_f32 v[38:39], v[38:39], v[2:3] op_sel_hi:[1,0]
	v_bfe_u32 v11, v43, 16, 1
	v_bfe_u32 v56, v42, 16, 1
	v_bfe_u32 v57, v41, 16, 1
	v_bfe_u32 v58, v40, 16, 1
	v_add3_u32 v40, v40, v58, s33
	v_add3_u32 v41, v41, v57, s33
	v_add3_u32 v42, v42, v56, s33
	v_add3_u32 v11, v43, v11, s33
	v_bfe_u32 v43, v36, 16, 1
	v_bfe_u32 v56, v37, 16, 1
	v_bfe_u32 v57, v38, 16, 1
	v_bfe_u32 v58, v39, 16, 1
	v_add3_u32 v58, v39, v58, s33
	v_add3_u32 v57, v38, v57, s33
	v_add3_u32 v56, v37, v56, s33
	v_add3_u32 v43, v36, v43, s33
	ds_read2_b64 v[36:39], v3 offset0:24 offset1:28
	v_lshrrev_b32_e32 v59, 16, v43
	v_lshrrev_b32_e32 v56, 16, v56
	v_lshrrev_b32_e32 v57, 16, v57
	v_lshrrev_b32_e32 v43, 16, v58
	v_and_or_b32 v43, v11, s29, v43
	v_and_or_b32 v42, v42, s29, v57
	v_and_or_b32 v41, v41, s29, v56
	v_and_or_b32 v40, v40, s29, v59
	ds_read2_b64 v[56:59], v61 offset0:120 offset1:124
	s_waitcnt lgkmcnt(1)
	v_mfma_f32_16x16x32_bf16 v[36:39], v[36:39], v[40:43], v[44:47]
	s_nop 2
	ds_read2_b64 v[44:47], v10 offset0:56 offset1:60
	s_waitcnt lgkmcnt(0)
	v_mfma_f32_16x16x32_bf16 v[44:47], v[44:47], v[40:43], v[52:55]
	s_nop 2
	ds_read2_b64 v[52:55], v60 offset0:88 offset1:92
	s_waitcnt lgkmcnt(0)
	v_mfma_f32_16x16x32_bf16 v[52:55], v[52:55], v[40:43], v[62:65]
	v_mfma_f32_16x16x32_bf16 v[40:43], v[56:59], v[40:43], v[48:51]
	v_mul_f32_e64 v32, v32, v2
	v_mul_f32_e64 v33, v33, v2
	v_pk_mul_f32 v[34:35], v[34:35], v[2:3] op_sel_hi:[1,0]
	v_pk_mul_f32 v[28:29], v[28:29], v[2:3] op_sel_hi:[1,0]
	v_pk_mul_f32 v[30:31], v[30:31], v[2:3] op_sel_hi:[1,0]
	v_bfe_u32 v11, v35, 16, 1
	v_bfe_u32 v48, v34, 16, 1
	v_bfe_u32 v49, v33, 16, 1
	v_bfe_u32 v50, v32, 16, 1
	v_add3_u32 v32, v32, v50, s33
	v_add3_u32 v33, v33, v49, s33
	v_add3_u32 v34, v34, v48, s33
	v_add3_u32 v11, v35, v11, s33
	v_bfe_u32 v35, v28, 16, 1
	v_bfe_u32 v48, v29, 16, 1
	v_bfe_u32 v49, v30, 16, 1
	v_bfe_u32 v50, v31, 16, 1
	v_add3_u32 v50, v31, v50, s33
	v_add3_u32 v49, v30, v49, s33
	v_add3_u32 v48, v29, v48, s33
	v_add3_u32 v35, v28, v35, s33
	ds_read2_b64 v[28:31], v3 offset0:32 offset1:36
	v_lshrrev_b32_e32 v51, 16, v35
	v_lshrrev_b32_e32 v48, 16, v48
	v_lshrrev_b32_e32 v49, 16, v49
	v_lshrrev_b32_e32 v35, 16, v50
	v_and_or_b32 v35, v11, s29, v35
	v_and_or_b32 v34, v34, s29, v49
	v_and_or_b32 v33, v33, s29, v48
	v_and_or_b32 v32, v32, s29, v51
	ds_read2_b64 v[48:51], v61 offset0:128 offset1:132
	s_waitcnt lgkmcnt(1)
	v_mfma_f32_16x16x32_bf16 v[28:31], v[28:31], v[32:35], v[36:39]
	s_nop 2
	ds_read2_b64 v[36:39], v10 offset0:64 offset1:68
	s_waitcnt lgkmcnt(0)
	v_mfma_f32_16x16x32_bf16 v[36:39], v[36:39], v[32:35], v[44:47]
	s_nop 2
	ds_read2_b64 v[44:47], v60 offset0:96 offset1:100
	s_waitcnt lgkmcnt(0)
	v_mfma_f32_16x16x32_bf16 v[44:47], v[44:47], v[32:35], v[52:55]
	v_mfma_f32_16x16x32_bf16 v[32:35], v[48:51], v[32:35], v[40:43]
	v_mul_f32_e64 v24, v24, v2
	v_mul_f32_e64 v25, v25, v2
	v_pk_mul_f32 v[26:27], v[26:27], v[2:3] op_sel_hi:[1,0]
	v_pk_mul_f32 v[20:21], v[20:21], v[2:3] op_sel_hi:[1,0]
	v_pk_mul_f32 v[22:23], v[22:23], v[2:3] op_sel_hi:[1,0]
	v_bfe_u32 v11, v27, 16, 1
	v_bfe_u32 v40, v26, 16, 1
	v_bfe_u32 v41, v25, 16, 1
	v_bfe_u32 v42, v24, 16, 1
	v_add3_u32 v24, v24, v42, s33
	v_add3_u32 v25, v25, v41, s33
	v_add3_u32 v26, v26, v40, s33
	v_add3_u32 v11, v27, v11, s33
	v_bfe_u32 v27, v20, 16, 1
	v_bfe_u32 v40, v21, 16, 1
	v_bfe_u32 v41, v22, 16, 1
	v_bfe_u32 v42, v23, 16, 1
	v_add3_u32 v42, v23, v42, s33
	v_add3_u32 v41, v22, v41, s33
	v_add3_u32 v40, v21, v40, s33
	v_add3_u32 v27, v20, v27, s33
	ds_read2_b64 v[20:23], v3 offset0:40 offset1:44
	v_lshrrev_b32_e32 v43, 16, v27
	v_lshrrev_b32_e32 v40, 16, v40
	v_lshrrev_b32_e32 v41, 16, v41
	v_lshrrev_b32_e32 v27, 16, v42
	v_and_or_b32 v27, v11, s29, v27
	v_and_or_b32 v26, v26, s29, v41
	v_and_or_b32 v25, v25, s29, v40
	v_and_or_b32 v24, v24, s29, v43
	ds_read2_b64 v[40:43], v61 offset0:136 offset1:140
	s_waitcnt lgkmcnt(1)
	v_mfma_f32_16x16x32_bf16 v[20:23], v[20:23], v[24:27], v[28:31]
	s_nop 2
	ds_read2_b64 v[28:31], v10 offset0:72 offset1:76
	s_waitcnt lgkmcnt(0)
	v_mfma_f32_16x16x32_bf16 v[28:31], v[28:31], v[24:27], v[36:39]
	s_nop 2
	ds_read2_b64 v[36:39], v60 offset0:104 offset1:108
	s_waitcnt lgkmcnt(0)
	v_mfma_f32_16x16x32_bf16 v[36:39], v[36:39], v[24:27], v[44:47]
	v_mfma_f32_16x16x32_bf16 v[24:27], v[40:43], v[24:27], v[32:35]
	v_mul_f32_e64 v16, v16, v2
	v_mul_f32_e64 v17, v17, v2
	v_pk_mul_f32 v[18:19], v[18:19], v[2:3] op_sel_hi:[1,0]
	v_pk_mul_f32 v[12:13], v[12:13], v[2:3] op_sel_hi:[1,0]
	v_pk_mul_f32 v[14:15], v[14:15], v[2:3] op_sel_hi:[1,0]
	v_bfe_u32 v11, v19, 16, 1
	v_bfe_u32 v32, v18, 16, 1
	v_bfe_u32 v33, v17, 16, 1
	v_bfe_u32 v34, v16, 16, 1
	v_add3_u32 v16, v16, v34, s33
	v_add3_u32 v17, v17, v33, s33
	v_add3_u32 v18, v18, v32, s33
	v_add3_u32 v11, v19, v11, s33
	v_bfe_u32 v19, v12, 16, 1
	v_bfe_u32 v32, v13, 16, 1
	v_bfe_u32 v33, v14, 16, 1
	v_bfe_u32 v34, v15, 16, 1
	v_add3_u32 v34, v15, v34, s33
	v_add3_u32 v33, v14, v33, s33
	v_add3_u32 v32, v13, v32, s33
	v_add3_u32 v19, v12, v19, s33
	ds_read2_b64 v[12:15], v3 offset0:48 offset1:52
	v_lshrrev_b32_e32 v35, 16, v19
	v_lshrrev_b32_e32 v32, 16, v32
	v_lshrrev_b32_e32 v33, 16, v33
	v_lshrrev_b32_e32 v19, 16, v34
	v_and_or_b32 v19, v11, s29, v19
	v_and_or_b32 v18, v18, s29, v33
	v_and_or_b32 v17, v17, s29, v32
	v_and_or_b32 v16, v16, s29, v35
	ds_read2_b64 v[32:35], v61 offset0:144 offset1:148
	s_waitcnt lgkmcnt(1)
	v_mfma_f32_16x16x32_bf16 v[12:15], v[12:15], v[16:19], v[20:23]
	s_nop 2
	ds_read2_b64 v[20:23], v10 offset0:80 offset1:84
	s_waitcnt lgkmcnt(0)
	v_mfma_f32_16x16x32_bf16 v[20:23], v[20:23], v[16:19], v[28:31]
	s_nop 2
	ds_read2_b64 v[28:31], v60 offset0:112 offset1:116
	s_waitcnt lgkmcnt(0)
	v_mfma_f32_16x16x32_bf16 v[28:31], v[28:31], v[16:19], v[36:39]
	v_mfma_f32_16x16x32_bf16 v[16:19], v[32:35], v[16:19], v[24:27]
	v_mul_f32_e64 v8, v8, v2
	v_mul_f32_e64 v9, v9, v2
	v_pk_mul_f32 v[6:7], v[6:7], v[2:3] op_sel_hi:[1,0]
	v_pk_mul_f32 v[4:5], v[4:5], v[2:3] op_sel_hi:[1,0]
	v_pk_mul_f32 v[0:1], v[0:1], v[2:3] op_sel_hi:[1,0]
	v_bfe_u32 v2, v7, 16, 1
	v_bfe_u32 v24, v9, 16, 1
	v_bfe_u32 v25, v8, 16, 1
	v_add3_u32 v8, v8, v25, s33
	v_add3_u32 v9, v9, v24, s33
	v_add3_u32 v7, v7, v2, s33
	v_bfe_u32 v2, v4, 16, 1
	v_bfe_u32 v24, v0, 16, 1
	v_bfe_u32 v25, v1, 16, 1
	v_add3_u32 v25, v1, v25, s33
	v_add3_u32 v24, v0, v24, s33
	v_add3_u32 v4, v4, v2, s33
	ds_read2_b64 v[0:3], v3 offset0:56 offset1:60
	v_bfe_u32 v11, v6, 16, 1
	v_add3_u32 v6, v6, v11, s33
	v_bfe_u32 v11, v5, 16, 1
	v_add3_u32 v5, v5, v11, s33
	v_lshrrev_b32_e32 v4, 16, v4
	v_lshrrev_b32_e32 v5, 16, v5
	v_lshrrev_b32_e32 v11, 16, v24
	v_lshrrev_b32_e32 v24, 16, v25
	v_and_or_b32 v27, v7, s29, v24
	v_and_or_b32 v26, v6, s29, v11
	v_and_or_b32 v25, v9, s29, v5
	v_and_or_b32 v24, v8, s29, v4
	s_waitcnt lgkmcnt(0)
	s_nop 0
	v_mfma_f32_16x16x32_bf16 v[12:15], v[0:3], v[24:27], v[12:15]
	ds_read2_b64 v[0:3], v10 offset0:88 offset1:92
	s_waitcnt lgkmcnt(0)
	v_mfma_f32_16x16x32_bf16 v[8:11], v[0:3], v[24:27], v[20:23]
	ds_read2_b64 v[0:3], v60 offset0:120 offset1:124
	s_waitcnt lgkmcnt(0)
	v_mfma_f32_16x16x32_bf16 v[4:7], v[0:3], v[24:27], v[28:31]
	ds_read2_b64 v[0:3], v61 offset0:152 offset1:156
	s_waitcnt lgkmcnt(0)
	v_mfma_f32_16x16x32_bf16 v[0:3], v[0:3], v[24:27], v[16:19]
	s_and_b64 exec, exec, s[0:1]
	s_cbranch_execz .LBB0_153
	s_lshl_b32 s0, s17, 11
	v_bfe_u32 v18, v12, 16, 1
	s_add_u32 s0, s6, s0
	v_add3_u32 v12, v12, v18, s33
	v_bfe_u32 v18, v13, 16, 1
	s_addc_u32 s1, s7, 0
	v_add3_u32 v13, v13, v18, s33
	v_lshrrev_b32_e32 v12, 16, v12
	s_add_u32 s0, s0, s12
	v_and_or_b32 v12, v13, s29, v12
	v_bfe_u32 v13, v14, 16, 1
	s_addc_u32 s1, s1, 0
	v_lshlrev_b64 v[16:17], 11, v[68:69]
	v_add3_u32 v13, v14, v13, s33
	v_bfe_u32 v14, v15, 16, 1
	v_lshl_add_u64 v[16:17], s[0:1], 0, v[16:17]
	v_mov_b32_e32 v71, v80
	v_add3_u32 v14, v15, v14, s33
	v_lshrrev_b32_e32 v13, 16, v13
	v_lshl_add_u64 v[16:17], v[16:17], 0, v[70:71]
	v_and_or_b32 v13, v14, s29, v13
	global_store_dwordx2 v[16:17], v[12:13], off offset:1536
	v_bfe_u32 v12, v8, 16, 1
	v_add3_u32 v8, v8, v12, s33
	v_bfe_u32 v12, v9, 16, 1
	v_add3_u32 v9, v9, v12, s33
	v_lshrrev_b32_e32 v8, 16, v8
	v_and_or_b32 v8, v9, s29, v8
	v_bfe_u32 v9, v10, 16, 1
	v_add3_u32 v9, v10, v9, s33
	v_bfe_u32 v10, v11, 16, 1
	v_add3_u32 v10, v11, v10, s33
	v_lshrrev_b32_e32 v9, 16, v9
	v_and_or_b32 v9, v10, s29, v9
	global_store_dwordx2 v[16:17], v[8:9], off offset:1568
	v_bfe_u32 v8, v4, 16, 1
	v_add3_u32 v4, v4, v8, s33
	v_bfe_u32 v8, v5, 16, 1
	v_add3_u32 v5, v5, v8, s33
	v_lshrrev_b32_e32 v4, 16, v4
	v_and_or_b32 v4, v5, s29, v4
	v_bfe_u32 v5, v6, 16, 1
	v_add3_u32 v5, v6, v5, s33
	v_bfe_u32 v6, v7, 16, 1
	v_add3_u32 v6, v7, v6, s33
	v_lshrrev_b32_e32 v5, 16, v5
	v_and_or_b32 v5, v6, s29, v5
	global_store_dwordx2 v[16:17], v[4:5], off offset:1600
	v_bfe_u32 v4, v0, 16, 1
	v_add3_u32 v0, v0, v4, s33
	v_bfe_u32 v4, v1, 16, 1
	v_add3_u32 v1, v1, v4, s33
	v_lshrrev_b32_e32 v0, 16, v0
	v_and_or_b32 v0, v1, s29, v0
	v_bfe_u32 v1, v2, 16, 1
	v_add3_u32 v1, v2, v1, s33
	v_bfe_u32 v2, v3, 16, 1
	v_add3_u32 v2, v3, v2, s33
	v_lshrrev_b32_e32 v1, 16, v1
	v_and_or_b32 v1, v2, s29, v1
	global_store_dwordx2 v[16:17], v[0:1], off offset:1632

.LBB0_245:
	s_or_b64 exec, exec, s[2:3]
	v_and_b32_e32 v45, 15, v13
	v_mad_u32_u24 v43, v45, s14, v44
	v_mov_b32_e32 v1, v4
	v_mov_b32_e32 v33, v6
	ds_read_b128 v[116:119], v43
	ds_read_b128 v[120:123], v43 offset:64
	ds_read_b128 v[124:127], v43 offset:2304
	ds_read_b128 v[128:131], v43 offset:2368
	ds_read_b128 v[132:135], v43 offset:4608
	ds_read_b128 v[136:139], v43 offset:4672
	ds_read_b128 v[140:143], v43 offset:6912
	ds_read_b128 v[144:147], v43 offset:6976
	ds_read_b128 v[148:151], v43 offset:9216
	ds_read_b128 v[152:155], v43 offset:9280
	ds_read_b128 v[156:159], v43 offset:11520
	ds_read_b128 v[160:163], v43 offset:11584
	s_waitcnt lgkmcnt(6)
	v_mfma_f32_16x16x32_bf16 v[36:39], v[116:119], v[0:3], 0
	v_mfma_f32_16x16x32_bf16 v[28:31], v[124:127], v[0:3], 0
	v_mfma_f32_16x16x32_bf16 v[24:27], v[132:135], v[0:3], 0
	v_mfma_f32_16x16x32_bf16 v[36:39], v[120:123], v[32:35], v[36:39]
	v_mfma_f32_16x16x32_bf16 v[28:31], v[128:131], v[32:35], v[28:31]
	v_mfma_f32_16x16x32_bf16 v[24:27], v[136:139], v[32:35], v[24:27]
	ds_read_b128 v[116:119], v43 offset:13824
	ds_read_b128 v[120:123], v43 offset:13888
	ds_read_b128 v[124:127], v43 offset:16128
	ds_read_b128 v[128:131], v43 offset:16192
	s_waitcnt lgkmcnt(4)
	v_mfma_f32_16x16x32_bf16 v[20:23], v[140:143], v[0:3], 0
	v_mfma_f32_16x16x32_bf16 v[16:19], v[148:151], v[0:3], 0
	v_mfma_f32_16x16x32_bf16 v[12:15], v[156:159], v[0:3], 0
	v_mfma_f32_16x16x32_bf16 v[20:23], v[144:147], v[32:35], v[20:23]
	v_mfma_f32_16x16x32_bf16 v[16:19], v[152:155], v[32:35], v[16:19]
	v_mfma_f32_16x16x32_bf16 v[12:15], v[160:163], v[32:35], v[12:15]
	s_waitcnt lgkmcnt(0)
	v_mfma_f32_16x16x32_bf16 v[8:11], v[116:119], v[0:3], 0
	v_mfma_f32_16x16x32_bf16 v[4:7], v[124:127], v[0:3], 0
	v_mfma_f32_16x16x32_bf16 v[8:11], v[120:123], v[32:35], v[8:11]
	v_mfma_f32_16x16x32_bf16 v[4:7], v[128:131], v[32:35], v[4:7]
	ds_read_b128 v[116:119], v43 offset:18432
	ds_read_b128 v[120:123], v43 offset:18496
	s_waitcnt lgkmcnt(0)
	v_mfma_f32_16x16x32_bf16 v[124:127], v[116:119], v[0:3], 0
	v_mfma_f32_16x16x32_bf16 v[0:3], v[120:123], v[32:35], v[124:127]
	v_mov_b32_e32 v43, 0
	s_and_saveexec_b64 s[2:3], s[0:1]
	s_cbranch_execz .LBB0_247
	v_readlane_b32 s4, v249, 55
	v_readlane_b32 s5, v249, 56
	s_lshl_b64 s[4:5], s[4:5], 2
	s_add_u32 s4, s12, s4
	s_addc_u32 s5, s13, s5
	s_lshl_b32 s8, s18, 2
	s_add_u32 s4, s4, s8
	s_addc_u32 s5, s5, 0
	v_ashrrev_i32_e32 v43, 31, v42
	v_lshl_add_u64 v[32:33], v[42:43], 2, s[4:5]
	global_load_dword v43, v[32:33], off

.LBB0_256:
	ds_read_b128 v[116:119], v82
	ds_read_b128 v[120:123], v82 offset:64
	ds_read_b128 v[124:127], v82 offset:2304
	ds_read_b128 v[128:131], v82 offset:2368
	ds_read_b128 v[132:135], v82 offset:4608
	ds_read_b128 v[136:139], v82 offset:4672
	ds_read_b128 v[140:143], v82 offset:6912
	ds_read_b128 v[144:147], v82 offset:6976
	ds_read_b128 v[148:151], v82 offset:9216
	ds_read_b128 v[152:155], v82 offset:9280
	ds_read_b128 v[156:159], v82 offset:11520
	ds_read_b128 v[160:163], v82 offset:11584
	s_waitcnt lgkmcnt(6)
	v_mfma_f32_16x16x32_bf16 v[68:71], v[116:119], v[72:75], 0
	v_mfma_f32_16x16x32_bf16 v[64:67], v[124:127], v[72:75], 0
	v_mfma_f32_16x16x32_bf16 v[60:63], v[132:135], v[72:75], 0
	v_mfma_f32_16x16x32_bf16 v[68:71], v[120:123], v[8:11], v[68:71]
	v_mfma_f32_16x16x32_bf16 v[64:67], v[128:131], v[8:11], v[64:67]
	v_mfma_f32_16x16x32_bf16 v[60:63], v[136:139], v[8:11], v[60:63]
	ds_read_b128 v[116:119], v82 offset:13824
	ds_read_b128 v[120:123], v82 offset:13888
	ds_read_b128 v[124:127], v82 offset:16128
	ds_read_b128 v[128:131], v82 offset:16192
	ds_read_b128 v[132:135], v82 offset:18432
	ds_read_b128 v[136:139], v82 offset:18496
	s_waitcnt lgkmcnt(6)
	v_mfma_f32_16x16x32_bf16 v[56:59], v[140:143], v[72:75], 0
	v_mfma_f32_16x16x32_bf16 v[52:55], v[148:151], v[72:75], 0
	v_mfma_f32_16x16x32_bf16 v[48:51], v[156:159], v[72:75], 0
	v_mfma_f32_16x16x32_bf16 v[56:59], v[144:147], v[8:11], v[56:59]
	v_mfma_f32_16x16x32_bf16 v[52:55], v[152:155], v[8:11], v[52:55]
	v_mfma_f32_16x16x32_bf16 v[48:51], v[160:163], v[8:11], v[48:51]
	ds_read_b128 v[140:143], v82 offset:20736
	ds_read_b128 v[144:147], v82 offset:20800
	ds_read_b128 v[148:151], v82 offset:23040
	ds_read_b128 v[152:155], v82 offset:23104
	ds_read_b128 v[156:159], v82 offset:25344
	ds_read_b128 v[160:163], v82 offset:25408
	s_waitcnt lgkmcnt(6)
	v_mfma_f32_16x16x32_bf16 v[44:47], v[116:119], v[72:75], 0
	v_mfma_f32_16x16x32_bf16 v[40:43], v[124:127], v[72:75], 0
	v_mfma_f32_16x16x32_bf16 v[36:39], v[132:135], v[72:75], 0
	v_mfma_f32_16x16x32_bf16 v[44:47], v[120:123], v[8:11], v[44:47]
	v_mfma_f32_16x16x32_bf16 v[40:43], v[128:131], v[8:11], v[40:43]
	v_mfma_f32_16x16x32_bf16 v[36:39], v[136:139], v[8:11], v[36:39]
	ds_read_b128 v[116:119], v82 offset:27648
	ds_read_b128 v[120:123], v82 offset:27712
	ds_read_b128 v[124:127], v82 offset:29952
	ds_read_b128 v[128:131], v82 offset:30016
	ds_read_b128 v[132:135], v82 offset:32256
	ds_read_b128 v[136:139], v82 offset:32320
	s_waitcnt lgkmcnt(6)
	v_mfma_f32_16x16x32_bf16 v[32:35], v[140:143], v[72:75], 0
	v_mfma_f32_16x16x32_bf16 v[28:31], v[148:151], v[72:75], 0
	v_mfma_f32_16x16x32_bf16 v[24:27], v[156:159], v[72:75], 0
	v_mfma_f32_16x16x32_bf16 v[32:35], v[144:147], v[8:11], v[32:35]
	v_mfma_f32_16x16x32_bf16 v[28:31], v[152:155], v[8:11], v[28:31]
	v_mfma_f32_16x16x32_bf16 v[24:27], v[160:163], v[8:11], v[24:27]
	s_waitcnt lgkmcnt(0)
	v_mfma_f32_16x16x32_bf16 v[20:23], v[116:119], v[72:75], 0
	v_mfma_f32_16x16x32_bf16 v[16:19], v[124:127], v[72:75], 0
	v_mfma_f32_16x16x32_bf16 v[12:15], v[132:135], v[72:75], 0
	v_mfma_f32_16x16x32_bf16 v[20:23], v[120:123], v[8:11], v[20:23]
	v_mfma_f32_16x16x32_bf16 v[16:19], v[128:131], v[8:11], v[16:19]
	v_mfma_f32_16x16x32_bf16 v[12:15], v[136:139], v[8:11], v[12:15]
	ds_read_b128 v[116:119], v82 offset:34560
	ds_read_b128 v[120:123], v82 offset:34624
	s_waitcnt lgkmcnt(0)
	v_mfma_f32_16x16x32_bf16 v[124:127], v[116:119], v[72:75], 0
	v_mfma_f32_16x16x32_bf16 v[8:11], v[120:123], v[8:11], v[124:127]
	s_nop 4
	v_mul_f32_e32 v72, 0x3e000000, v68
	v_mul_f32_e32 v73, 0x3e000000, v69
	s_mov_b32 s2, 0xff61b1e6
	v_max3_f32 v72, v72, s2, v73
	v_mul_f32_e32 v73, 0x3e000000, v70
	v_mul_f32_e32 v74, 0x3e000000, v71
	v_max3_f32 v72, v72, v73, v74
	v_mul_f32_e32 v73, 0x3e000000, v64
	v_mul_f32_e32 v74, 0x3e000000, v65
	v_max3_f32 v72, v72, v73, v74
	v_mul_f32_e32 v73, 0x3e000000, v66
	v_mul_f32_e32 v74, 0x3e000000, v67
	v_max3_f32 v72, v72, v73, v74
	v_mul_f32_e32 v73, 0x3e000000, v60
	v_mul_f32_e32 v74, 0x3e000000, v61
	v_max3_f32 v72, v72, v73, v74
	v_mul_f32_e32 v73, 0x3e000000, v62
	v_mul_f32_e32 v74, 0x3e000000, v63
	v_max3_f32 v72, v72, v73, v74
	v_mul_f32_e32 v73, 0x3e000000, v56
	v_mul_f32_e32 v74, 0x3e000000, v57
	v_max3_f32 v72, v72, v73, v74
	v_mul_f32_e32 v73, 0x3e000000, v58
	v_mul_f32_e32 v74, 0x3e000000, v59
	v_max3_f32 v72, v72, v73, v74
	v_mul_f32_e32 v73, 0x3e000000, v52
	v_mul_f32_e32 v74, 0x3e000000, v53
	v_max3_f32 v72, v72, v73, v74
	v_mul_f32_e32 v73, 0x3e000000, v54
	v_mul_f32_e32 v74, 0x3e000000, v55
	v_max3_f32 v72, v72, v73, v74
	v_mul_f32_e32 v73, 0x3e000000, v48
	v_mul_f32_e32 v74, 0x3e000000, v49
	v_max3_f32 v72, v72, v73, v74
	v_mul_f32_e32 v73, 0x3e000000, v50
	v_mul_f32_e32 v74, 0x3e000000, v51
	v_max3_f32 v72, v72, v73, v74
	v_mul_f32_e32 v73, 0x3e000000, v44
	v_mul_f32_e32 v74, 0x3e000000, v45
	v_max3_f32 v72, v72, v73, v74
	v_mul_f32_e32 v73, 0x3e000000, v46
	v_mul_f32_e32 v74, 0x3e000000, v47
	v_max3_f32 v72, v72, v73, v74
	v_mul_f32_e32 v73, 0x3e000000, v40
	v_mul_f32_e32 v74, 0x3e000000, v41
	v_max3_f32 v72, v72, v73, v74
	v_mul_f32_e32 v73, 0x3e000000, v42
	v_mul_f32_e32 v74, 0x3e000000, v43
	v_max3_f32 v72, v72, v73, v74
	v_mul_f32_e32 v73, 0x3e000000, v36
	v_mul_f32_e32 v74, 0x3e000000, v37
	v_max3_f32 v72, v72, v73, v74
	v_mul_f32_e32 v73, 0x3e000000, v38
	v_mul_f32_e32 v74, 0x3e000000, v39
	v_max3_f32 v72, v72, v73, v74
	v_mul_f32_e32 v73, 0x3e000000, v32
	v_mul_f32_e32 v74, 0x3e000000, v33
	v_max3_f32 v72, v72, v73, v74
	v_mul_f32_e32 v73, 0x3e000000, v34
	v_mul_f32_e32 v74, 0x3e000000, v35
	v_max3_f32 v72, v72, v73, v74
	v_mul_f32_e32 v73, 0x3e000000, v28
	v_mul_f32_e32 v74, 0x3e000000, v29
	v_max3_f32 v72, v72, v73, v74
	v_mul_f32_e32 v73, 0x3e000000, v30
	v_mul_f32_e32 v74, 0x3e000000, v31
	v_max3_f32 v72, v72, v73, v74
	v_mul_f32_e32 v73, 0x3e000000, v24
	v_mul_f32_e32 v74, 0x3e000000, v25
	v_max3_f32 v72, v72, v73, v74
	v_mul_f32_e32 v73, 0x3e000000, v26
	v_mul_f32_e32 v74, 0x3e000000, v27
	v_max3_f32 v72, v72, v73, v74
	v_mul_f32_e32 v73, 0x3e000000, v20
	v_mul_f32_e32 v74, 0x3e000000, v21
	v_max3_f32 v72, v72, v73, v74
	v_mul_f32_e32 v73, 0x3e000000, v22
	v_mul_f32_e32 v74, 0x3e000000, v23
	v_max3_f32 v72, v72, v73, v74
	v_mul_f32_e32 v73, 0x3e000000, v16
	v_mul_f32_e32 v74, 0x3e000000, v17
	v_max3_f32 v72, v72, v73, v74
	v_mul_f32_e32 v73, 0x3e000000, v18
	v_mul_f32_e32 v74, 0x3e000000, v19
	v_max3_f32 v72, v72, v73, v74
	v_mul_f32_e32 v73, 0x3e000000, v12
	v_mul_f32_e32 v74, 0x3e000000, v13
	v_max3_f32 v72, v72, v73, v74
	v_mul_f32_e32 v73, 0x3e000000, v14
	v_mul_f32_e32 v74, 0x3e000000, v15
	v_max3_f32 v72, v72, v73, v74
	v_mul_f32_e32 v73, 0x3e000000, v8
	v_mul_f32_e32 v74, 0x3e000000, v9
	v_max3_f32 v72, v72, v73, v74
	v_mul_f32_e32 v73, 0x3e000000, v10
	v_mul_f32_e32 v74, 0x3e000000, v11
	v_max3_f32 v72, v72, v73, v74
	ds_bpermute_b32 v73, v83, v72
	s_mov_b32 s2, 0x3e000000
	s_waitcnt lgkmcnt(0)
	v_max_f32_e32 v73, v73, v73
	v_max_f32_e32 v72, v72, v73
	ds_bpermute_b32 v73, v84, v72
	s_waitcnt lgkmcnt(0)
	v_max_f32_e32 v73, v73, v73
	v_max_f32_e32 v86, v72, v73
	v_fma_f32 v68, v68, s2, -v86
	v_fma_f32 v69, v69, s2, -v86
	v_mul_f32_e32 v68, 0x3fb8aa3b, v68
	v_mul_f32_e32 v69, 0x3fb8aa3b, v69
	v_exp_f32_e32 v68, v68
	v_exp_f32_e32 v72, v69
	v_fma_f32 v69, v70, s2, -v86
	v_mul_f32_e32 v69, 0x3fb8aa3b, v69
	v_fma_f32 v70, v71, s2, -v86
	v_exp_f32_e32 v69, v69
	v_mul_f32_e32 v70, 0x3fb8aa3b, v70
	v_exp_f32_e32 v73, v70
	v_add_f32_e32 v70, 0, v68
	v_add_f32_e32 v70, v72, v70
	v_fma_f32 v64, v64, s2, -v86
	v_add_f32_e32 v70, v69, v70
	v_mul_f32_e32 v64, 0x3fb8aa3b, v64
	v_add_f32_e32 v87, v73, v70
	v_exp_f32_e32 v70, v64
	v_fma_f32 v64, v65, s2, -v86
	v_mul_f32_e32 v64, 0x3fb8aa3b, v64
	v_exp_f32_e32 v74, v64
	v_fma_f32 v64, v66, s2, -v86
	v_mul_f32_e32 v64, 0x3fb8aa3b, v64
	v_exp_f32_e32 v71, v64
	v_fma_f32 v64, v67, s2, -v86
	v_mul_f32_e32 v64, 0x3fb8aa3b, v64
	v_exp_f32_e32 v75, v64
	v_add_f32_e32 v64, v70, v87
	v_add_f32_e32 v64, v74, v64
	v_fma_f32 v60, v60, s2, -v86
	v_fma_f32 v61, v61, s2, -v86
	v_add_f32_e32 v64, v71, v64
	v_mul_f32_e32 v60, 0x3fb8aa3b, v60
	v_mul_f32_e32 v61, 0x3fb8aa3b, v61
	v_add_f32_e32 v66, v75, v64
	v_exp_f32_e32 v60, v60
	v_exp_f32_e32 v64, v61
	v_fma_f32 v61, v62, s2, -v86
	v_mul_f32_e32 v61, 0x3fb8aa3b, v61
	v_fma_f32 v62, v63, s2, -v86
	v_exp_f32_e32 v61, v61
	v_mul_f32_e32 v62, 0x3fb8aa3b, v62
	v_exp_f32_e32 v65, v62
	v_add_f32_e32 v62, v60, v66
	v_add_f32_e32 v62, v64, v62
	v_fma_f32 v56, v56, s2, -v86
	v_add_f32_e32 v62, v61, v62
	v_mul_f32_e32 v56, 0x3fb8aa3b, v56
	v_add_f32_e32 v87, v65, v62
	v_exp_f32_e32 v62, v56
	v_fma_f32 v56, v57, s2, -v86
	v_mul_f32_e32 v56, 0x3fb8aa3b, v56
	v_exp_f32_e32 v66, v56
	v_fma_f32 v56, v58, s2, -v86
	v_mul_f32_e32 v56, 0x3fb8aa3b, v56
	v_exp_f32_e32 v63, v56
	v_fma_f32 v56, v59, s2, -v86
	v_mul_f32_e32 v56, 0x3fb8aa3b, v56
	v_exp_f32_e32 v67, v56
	v_add_f32_e32 v56, v62, v87
	v_add_f32_e32 v56, v66, v56
	v_fma_f32 v52, v52, s2, -v86
	v_fma_f32 v53, v53, s2, -v86
	v_add_f32_e32 v56, v63, v56
	v_mul_f32_e32 v52, 0x3fb8aa3b, v52
	v_mul_f32_e32 v53, 0x3fb8aa3b, v53
	v_add_f32_e32 v58, v67, v56
	v_exp_f32_e32 v52, v52
	v_exp_f32_e32 v56, v53
	v_fma_f32 v53, v54, s2, -v86
	v_mul_f32_e32 v53, 0x3fb8aa3b, v53
	v_fma_f32 v54, v55, s2, -v86
	v_exp_f32_e32 v53, v53
	v_mul_f32_e32 v54, 0x3fb8aa3b, v54
	v_exp_f32_e32 v57, v54
	v_add_f32_e32 v54, v52, v58
	v_add_f32_e32 v54, v56, v54
	v_fma_f32 v48, v48, s2, -v86
	v_add_f32_e32 v54, v53, v54
	v_mul_f32_e32 v48, 0x3fb8aa3b, v48
	v_add_f32_e32 v87, v57, v54
	v_exp_f32_e32 v54, v48
	v_fma_f32 v48, v49, s2, -v86
	v_mul_f32_e32 v48, 0x3fb8aa3b, v48
	v_exp_f32_e32 v58, v48
	v_fma_f32 v48, v50, s2, -v86
	v_mul_f32_e32 v48, 0x3fb8aa3b, v48
	v_exp_f32_e32 v55, v48
	v_fma_f32 v48, v51, s2, -v86
	v_mul_f32_e32 v48, 0x3fb8aa3b, v48
	v_exp_f32_e32 v59, v48
	v_add_f32_e32 v48, v54, v87
	v_add_f32_e32 v48, v58, v48
	v_fma_f32 v44, v44, s2, -v86
	v_fma_f32 v45, v45, s2, -v86
	v_add_f32_e32 v48, v55, v48
	v_mul_f32_e32 v44, 0x3fb8aa3b, v44
	v_mul_f32_e32 v45, 0x3fb8aa3b, v45
	v_add_f32_e32 v50, v59, v48
	v_exp_f32_e32 v44, v44
	v_exp_f32_e32 v48, v45
	v_fma_f32 v45, v46, s2, -v86
	v_mul_f32_e32 v45, 0x3fb8aa3b, v45
	v_fma_f32 v46, v47, s2, -v86
	v_exp_f32_e32 v45, v45
	v_mul_f32_e32 v46, 0x3fb8aa3b, v46
	v_exp_f32_e32 v49, v46
	v_add_f32_e32 v46, v44, v50
	v_add_f32_e32 v46, v48, v46
	v_fma_f32 v40, v40, s2, -v86
	v_add_f32_e32 v46, v45, v46
	v_mul_f32_e32 v40, 0x3fb8aa3b, v40
	v_add_f32_e32 v87, v49, v46
	v_exp_f32_e32 v46, v40
	v_fma_f32 v40, v41, s2, -v86
	v_mul_f32_e32 v40, 0x3fb8aa3b, v40
	v_exp_f32_e32 v50, v40
	v_fma_f32 v40, v42, s2, -v86
	v_mul_f32_e32 v40, 0x3fb8aa3b, v40
	v_exp_f32_e32 v47, v40
	v_fma_f32 v40, v43, s2, -v86
	v_mul_f32_e32 v40, 0x3fb8aa3b, v40
	v_exp_f32_e32 v51, v40
	v_add_f32_e32 v40, v46, v87
	v_add_f32_e32 v40, v50, v40
	v_fma_f32 v36, v36, s2, -v86
	v_fma_f32 v37, v37, s2, -v86
	v_add_f32_e32 v40, v47, v40
	v_mul_f32_e32 v36, 0x3fb8aa3b, v36
	v_mul_f32_e32 v37, 0x3fb8aa3b, v37
	v_add_f32_e32 v42, v51, v40
	v_exp_f32_e32 v36, v36
	v_exp_f32_e32 v40, v37
	v_fma_f32 v37, v38, s2, -v86
	v_mul_f32_e32 v37, 0x3fb8aa3b, v37
	v_fma_f32 v38, v39, s2, -v86
	v_exp_f32_e32 v37, v37
	v_mul_f32_e32 v38, 0x3fb8aa3b, v38
	v_exp_f32_e32 v41, v38
	v_add_f32_e32 v38, v36, v42
	v_add_f32_e32 v38, v40, v38
	v_fma_f32 v32, v32, s2, -v86
	v_add_f32_e32 v38, v37, v38
	v_mul_f32_e32 v32, 0x3fb8aa3b, v32
	v_add_f32_e32 v87, v41, v38
	v_exp_f32_e32 v38, v32
	v_fma_f32 v32, v33, s2, -v86
	v_mul_f32_e32 v32, 0x3fb8aa3b, v32
	v_exp_f32_e32 v42, v32
	v_fma_f32 v32, v34, s2, -v86
	v_mul_f32_e32 v32, 0x3fb8aa3b, v32
	v_exp_f32_e32 v39, v32
	v_fma_f32 v32, v35, s2, -v86
	v_mul_f32_e32 v32, 0x3fb8aa3b, v32
	v_exp_f32_e32 v43, v32
	v_add_f32_e32 v32, v38, v87
	v_add_f32_e32 v32, v42, v32
	v_fma_f32 v28, v28, s2, -v86
	v_fma_f32 v29, v29, s2, -v86
	v_add_f32_e32 v32, v39, v32
	v_mul_f32_e32 v28, 0x3fb8aa3b, v28
	v_mul_f32_e32 v29, 0x3fb8aa3b, v29
	v_add_f32_e32 v34, v43, v32
	v_exp_f32_e32 v28, v28
	v_exp_f32_e32 v32, v29
	v_fma_f32 v29, v30, s2, -v86
	v_mul_f32_e32 v29, 0x3fb8aa3b, v29
	v_fma_f32 v30, v31, s2, -v86
	v_exp_f32_e32 v29, v29
	v_mul_f32_e32 v30, 0x3fb8aa3b, v30
	v_exp_f32_e32 v33, v30
	v_add_f32_e32 v30, v28, v34
	v_add_f32_e32 v30, v32, v30
	v_fma_f32 v24, v24, s2, -v86
	v_add_f32_e32 v30, v29, v30
	v_mul_f32_e32 v24, 0x3fb8aa3b, v24
	v_add_f32_e32 v87, v33, v30
	v_exp_f32_e32 v30, v24
	v_fma_f32 v24, v25, s2, -v86
	v_mul_f32_e32 v24, 0x3fb8aa3b, v24
	v_exp_f32_e32 v34, v24
	v_fma_f32 v24, v26, s2, -v86
	v_mul_f32_e32 v24, 0x3fb8aa3b, v24
	v_exp_f32_e32 v31, v24
	v_fma_f32 v24, v27, s2, -v86
	v_mul_f32_e32 v24, 0x3fb8aa3b, v24
	v_exp_f32_e32 v35, v24
	v_add_f32_e32 v24, v30, v87
	v_add_f32_e32 v24, v34, v24
	v_fma_f32 v20, v20, s2, -v86
	v_fma_f32 v21, v21, s2, -v86
	v_add_f32_e32 v24, v31, v24
	v_mul_f32_e32 v20, 0x3fb8aa3b, v20
	v_mul_f32_e32 v21, 0x3fb8aa3b, v21
	v_add_f32_e32 v26, v35, v24
	v_exp_f32_e32 v20, v20
	v_exp_f32_e32 v24, v21
	v_fma_f32 v21, v22, s2, -v86
	v_mul_f32_e32 v21, 0x3fb8aa3b, v21
	v_fma_f32 v22, v23, s2, -v86
	v_exp_f32_e32 v21, v21
	v_mul_f32_e32 v22, 0x3fb8aa3b, v22
	v_exp_f32_e32 v25, v22
	v_add_f32_e32 v22, v20, v26
	v_add_f32_e32 v22, v24, v22
	v_fma_f32 v16, v16, s2, -v86
	v_add_f32_e32 v22, v21, v22
	v_mul_f32_e32 v16, 0x3fb8aa3b, v16
	v_add_f32_e32 v87, v25, v22
	v_exp_f32_e32 v22, v16
	v_fma_f32 v16, v17, s2, -v86
	v_mul_f32_e32 v16, 0x3fb8aa3b, v16
	v_exp_f32_e32 v26, v16
	v_fma_f32 v16, v18, s2, -v86
	v_mul_f32_e32 v16, 0x3fb8aa3b, v16
	v_exp_f32_e32 v23, v16
	v_fma_f32 v16, v19, s2, -v86
	v_mul_f32_e32 v16, 0x3fb8aa3b, v16
	v_exp_f32_e32 v27, v16
	v_add_f32_e32 v16, v22, v87
	v_add_f32_e32 v16, v26, v16
	v_fma_f32 v12, v12, s2, -v86
	v_fma_f32 v13, v13, s2, -v86
	v_add_f32_e32 v16, v23, v16
	v_mul_f32_e32 v12, 0x3fb8aa3b, v12
	v_mul_f32_e32 v13, 0x3fb8aa3b, v13
	v_add_f32_e32 v18, v27, v16
	v_exp_f32_e32 v12, v12
	v_exp_f32_e32 v16, v13
	v_fma_f32 v13, v14, s2, -v86
	v_mul_f32_e32 v13, 0x3fb8aa3b, v13
	v_fma_f32 v14, v15, s2, -v86
	v_exp_f32_e32 v13, v13
	v_mul_f32_e32 v14, 0x3fb8aa3b, v14
	v_exp_f32_e32 v17, v14
	v_add_f32_e32 v14, v12, v18
	v_add_f32_e32 v14, v16, v14
	v_fma_f32 v8, v8, s2, -v86
	v_fma_f32 v9, v9, s2, -v86
	v_add_f32_e32 v14, v13, v14
	v_mul_f32_e32 v8, 0x3fb8aa3b, v8
	v_mul_f32_e32 v9, 0x3fb8aa3b, v9
	v_add_f32_e32 v18, v17, v14
	v_exp_f32_e32 v8, v8
	v_exp_f32_e32 v14, v9
	v_fma_f32 v9, v10, s2, -v86
	v_mul_f32_e32 v9, 0x3fb8aa3b, v9
	v_fma_f32 v10, v11, s2, -v86
	v_exp_f32_e32 v9, v9
	v_mul_f32_e32 v10, 0x3fb8aa3b, v10
	v_exp_f32_e32 v15, v10
	v_add_f32_e32 v10, v8, v18
	v_add_f32_e32 v10, v14, v10
	v_add_f32_e32 v10, v9, v10
	v_add_f32_e32 v10, v15, v10
	ds_bpermute_b32 v11, v83, v10
	s_waitcnt lgkmcnt(0)
	v_add_f32_e32 v10, v10, v11
	ds_bpermute_b32 v11, v84, v10
	s_waitcnt lgkmcnt(0)
	v_add_f32_e32 v10, v10, v11
	v_div_scale_f32 v11, s[2:3], v10, v10, 1.0
	v_rcp_f32_e32 v18, v11
	v_div_scale_f32 v19, vcc, 1.0, v10, 1.0
	v_fma_f32 v86, -v11, v18, 1.0
	v_fmac_f32_e32 v18, v86, v18
	v_mul_f32_e32 v86, v19, v18
	v_fma_f32 v87, -v11, v86, v19
	v_fmac_f32_e32 v86, v87, v18
	v_fma_f32 v11, -v11, v86, v19
	v_div_fmas_f32 v11, v11, v18, v86
	v_div_fixup_f32 v10, v11, v10, 1.0
	v_pk_mul_f32 v[18:19], v[68:69], v[10:11] op_sel_hi:[1,0]
	v_pk_mul_f32 v[68:69], v[72:73], v[10:11] op_sel_hi:[1,0]
	v_pk_mul_f32 v[72:73], v[74:75], v[10:11] op_sel_hi:[1,0]
	v_pk_mul_f32 v[70:71], v[70:71], v[10:11] op_sel_hi:[1,0]
	v_bfe_u32 v11, v73, 16, 1
	v_bfe_u32 v74, v72, 16, 1
	v_bfe_u32 v75, v69, 16, 1
	v_bfe_u32 v86, v68, 16, 1
	v_add3_u32 v73, v73, v11, s33
	v_bfe_u32 v11, v18, 16, 1
	v_add3_u32 v86, v68, v86, s33
	v_add3_u32 v87, v69, v75, s33
	v_add3_u32 v72, v72, v74, s33
	v_bfe_u32 v68, v19, 16, 1
	v_bfe_u32 v69, v70, 16, 1
	v_bfe_u32 v74, v71, 16, 1
	v_add3_u32 v18, v18, v11, s33
	v_add_u32_e32 v11, 0x9000, v85
	v_add3_u32 v74, v71, v74, s33
	v_add3_u32 v75, v70, v69, s33
	v_add3_u32 v19, v19, v68, s33
	ds_read2_b64 v[68:71], v11 offset1:4
	v_lshrrev_b32_e32 v18, 16, v18
	v_lshrrev_b32_e32 v19, 16, v19
	v_lshrrev_b32_e32 v88, 16, v75
	v_lshrrev_b32_e32 v74, 16, v74
	v_and_or_b32 v75, v73, s29, v74
	v_and_or_b32 v74, v72, s29, v88
	v_and_or_b32 v73, v87, s29, v19
	v_and_or_b32 v72, v86, s29, v18
	v_add_u32_e32 v18, 0xb000, v85
	s_waitcnt lgkmcnt(0)
	v_mfma_f32_16x16x32_bf16 v[86:89], v[68:71], v[72:75], 0
	ds_read2_b64 v[68:71], v18 offset0:32 offset1:36
	s_waitcnt lgkmcnt(0)
	v_mfma_f32_16x16x32_bf16 v[90:93], v[68:71], v[72:75], 0
	v_add_u32_e32 v68, 0xd000, v85
	v_add_u32_e32 v69, 0xf000, v85
	ds_read2_b64 v[94:97], v68 offset0:64 offset1:68
	ds_read2_b64 v[98:101], v69 offset0:96 offset1:100
	s_waitcnt lgkmcnt(1)
	v_mfma_f32_16x16x32_bf16 v[94:97], v[94:97], v[72:75], 0
	s_waitcnt lgkmcnt(0)
	v_mfma_f32_16x16x32_bf16 v[70:73], v[98:101], v[72:75], 0
	v_mul_f32_e64 v64, v64, v10
	v_mul_f32_e64 v65, v65, v10
	v_pk_mul_f32 v[66:67], v[66:67], v[10:11] op_sel_hi:[1,0]
	v_pk_mul_f32 v[60:61], v[60:61], v[10:11] op_sel_hi:[1,0]
	v_pk_mul_f32 v[62:63], v[62:63], v[10:11] op_sel_hi:[1,0]
	v_bfe_u32 v19, v67, 16, 1
	v_bfe_u32 v74, v66, 16, 1
	v_bfe_u32 v75, v65, 16, 1
	v_bfe_u32 v98, v64, 16, 1
	v_add3_u32 v64, v64, v98, s33
	v_add3_u32 v65, v65, v75, s33
	v_add3_u32 v66, v66, v74, s33
	v_add3_u32 v19, v67, v19, s33
	v_bfe_u32 v67, v60, 16, 1
	v_bfe_u32 v74, v61, 16, 1
	v_bfe_u32 v75, v62, 16, 1
	v_bfe_u32 v98, v63, 16, 1
	v_add3_u32 v98, v63, v98, s33
	v_add3_u32 v75, v62, v75, s33
	v_add3_u32 v74, v61, v74, s33
	v_add3_u32 v67, v60, v67, s33
	ds_read2_b64 v[60:63], v11 offset0:8 offset1:12
	v_lshrrev_b32_e32 v99, 16, v67
	v_lshrrev_b32_e32 v74, 16, v74
	v_lshrrev_b32_e32 v75, 16, v75
	v_lshrrev_b32_e32 v67, 16, v98
	v_and_or_b32 v67, v19, s29, v67
	v_and_or_b32 v66, v66, s29, v75
	v_and_or_b32 v65, v65, s29, v74
	v_and_or_b32 v64, v64, s29, v99
	s_waitcnt lgkmcnt(0)
	s_nop 0
	v_mfma_f32_16x16x32_bf16 v[60:63], v[60:63], v[64:67], v[86:89]
	s_nop 2
	ds_read2_b64 v[86:89], v18 offset0:40 offset1:44
	s_waitcnt lgkmcnt(0)
	v_mfma_f32_16x16x32_bf16 v[86:89], v[86:89], v[64:67], v[90:93]
	s_nop 2
	ds_read2_b64 v[90:93], v68 offset0:72 offset1:76
	s_waitcnt lgkmcnt(0)
	v_mfma_f32_16x16x32_bf16 v[90:93], v[90:93], v[64:67], v[94:97]
	s_nop 2
	ds_read2_b64 v[94:97], v69 offset0:104 offset1:108
	s_waitcnt lgkmcnt(0)
	v_mfma_f32_16x16x32_bf16 v[64:67], v[94:97], v[64:67], v[70:73]
	v_mul_f32_e64 v56, v56, v10
	v_mul_f32_e64 v57, v57, v10
	v_pk_mul_f32 v[58:59], v[58:59], v[10:11] op_sel_hi:[1,0]
	v_pk_mul_f32 v[52:53], v[52:53], v[10:11] op_sel_hi:[1,0]
	v_pk_mul_f32 v[54:55], v[54:55], v[10:11] op_sel_hi:[1,0]
	v_bfe_u32 v19, v59, 16, 1
	v_bfe_u32 v70, v58, 16, 1
	v_bfe_u32 v71, v57, 16, 1
	v_bfe_u32 v72, v56, 16, 1
	v_add3_u32 v56, v56, v72, s33
	v_add3_u32 v57, v57, v71, s33
	v_add3_u32 v58, v58, v70, s33
	v_add3_u32 v19, v59, v19, s33
	v_bfe_u32 v59, v52, 16, 1
	v_bfe_u32 v70, v53, 16, 1
	v_bfe_u32 v71, v54, 16, 1
	v_bfe_u32 v72, v55, 16, 1
	v_add3_u32 v72, v55, v72, s33
	v_add3_u32 v71, v54, v71, s33
	v_add3_u32 v70, v53, v70, s33
	v_add3_u32 v59, v52, v59, s33
	ds_read2_b64 v[52:55], v11 offset0:16 offset1:20
	v_lshrrev_b32_e32 v73, 16, v59
	v_lshrrev_b32_e32 v70, 16, v70
	v_lshrrev_b32_e32 v71, 16, v71
	v_lshrrev_b32_e32 v59, 16, v72
	v_and_or_b32 v59, v19, s29, v59
	v_and_or_b32 v58, v58, s29, v71
	v_and_or_b32 v57, v57, s29, v70
	v_and_or_b32 v56, v56, s29, v73
	ds_read2_b64 v[70:73], v68 offset0:80 offset1:84
	s_waitcnt lgkmcnt(1)
	v_mfma_f32_16x16x32_bf16 v[52:55], v[52:55], v[56:59], v[60:63]
	s_nop 2
	ds_read2_b64 v[60:63], v18 offset0:48 offset1:52
	s_waitcnt lgkmcnt(0)
	v_mfma_f32_16x16x32_bf16 v[60:63], v[60:63], v[56:59], v[86:89]
	s_nop 2
	ds_read2_b64 v[86:89], v69 offset0:112 offset1:116
	v_mfma_f32_16x16x32_bf16 v[70:73], v[70:73], v[56:59], v[90:93]
	s_waitcnt lgkmcnt(0)
	v_mfma_f32_16x16x32_bf16 v[56:59], v[86:89], v[56:59], v[64:67]
	v_mul_f32_e64 v48, v48, v10
	v_mul_f32_e64 v49, v49, v10
	v_pk_mul_f32 v[50:51], v[50:51], v[10:11] op_sel_hi:[1,0]
	v_pk_mul_f32 v[44:45], v[44:45], v[10:11] op_sel_hi:[1,0]
	v_pk_mul_f32 v[46:47], v[46:47], v[10:11] op_sel_hi:[1,0]
	v_bfe_u32 v19, v51, 16, 1
	v_bfe_u32 v64, v50, 16, 1
	v_bfe_u32 v65, v49, 16, 1
	v_bfe_u32 v66, v48, 16, 1
	v_add3_u32 v48, v48, v66, s33
	v_add3_u32 v49, v49, v65, s33
	v_add3_u32 v50, v50, v64, s33
	v_add3_u32 v19, v51, v19, s33
	v_bfe_u32 v51, v44, 16, 1
	v_bfe_u32 v64, v45, 16, 1
	v_bfe_u32 v65, v46, 16, 1
	v_bfe_u32 v66, v47, 16, 1
	v_add3_u32 v66, v47, v66, s33
	v_add3_u32 v65, v46, v65, s33
	v_add3_u32 v64, v45, v64, s33
	v_add3_u32 v51, v44, v51, s33
	ds_read2_b64 v[44:47], v11 offset0:24 offset1:28
	v_lshrrev_b32_e32 v67, 16, v51
	v_lshrrev_b32_e32 v64, 16, v64
	v_lshrrev_b32_e32 v65, 16, v65
	v_lshrrev_b32_e32 v51, 16, v66
	v_and_or_b32 v51, v19, s29, v51
	v_and_or_b32 v50, v50, s29, v65
	v_and_or_b32 v49, v49, s29, v64
	v_and_or_b32 v48, v48, s29, v67
	ds_read2_b64 v[64:67], v69 offset0:120 offset1:124
	s_waitcnt lgkmcnt(1)
	v_mfma_f32_16x16x32_bf16 v[44:47], v[44:47], v[48:51], v[52:55]
	s_nop 2
	ds_read2_b64 v[52:55], v18 offset0:56 offset1:60
	s_waitcnt lgkmcnt(0)
	v_mfma_f32_16x16x32_bf16 v[52:55], v[52:55], v[48:51], v[60:63]
	s_nop 2
	ds_read2_b64 v[60:63], v68 offset0:88 offset1:92
	s_waitcnt lgkmcnt(0)
	v_mfma_f32_16x16x32_bf16 v[60:63], v[60:63], v[48:51], v[70:73]
	v_mfma_f32_16x16x32_bf16 v[48:51], v[64:67], v[48:51], v[56:59]
	v_mul_f32_e64 v40, v40, v10
	v_mul_f32_e64 v41, v41, v10
	v_pk_mul_f32 v[42:43], v[42:43], v[10:11] op_sel_hi:[1,0]
	v_pk_mul_f32 v[36:37], v[36:37], v[10:11] op_sel_hi:[1,0]
	v_pk_mul_f32 v[38:39], v[38:39], v[10:11] op_sel_hi:[1,0]
	v_bfe_u32 v19, v43, 16, 1
	v_bfe_u32 v56, v42, 16, 1
	v_bfe_u32 v57, v41, 16, 1
	v_bfe_u32 v58, v40, 16, 1
	v_add3_u32 v40, v40, v58, s33
	v_add3_u32 v41, v41, v57, s33
	v_add3_u32 v42, v42, v56, s33
	v_add3_u32 v19, v43, v19, s33
	v_bfe_u32 v43, v36, 16, 1
	v_bfe_u32 v56, v37, 16, 1
	v_bfe_u32 v57, v38, 16, 1
	v_bfe_u32 v58, v39, 16, 1
	v_add3_u32 v58, v39, v58, s33
	v_add3_u32 v57, v38, v57, s33
	v_add3_u32 v56, v37, v56, s33
	v_add3_u32 v43, v36, v43, s33
	ds_read2_b64 v[36:39], v11 offset0:32 offset1:36
	v_lshrrev_b32_e32 v59, 16, v43
	v_lshrrev_b32_e32 v56, 16, v56
	v_lshrrev_b32_e32 v57, 16, v57
	v_lshrrev_b32_e32 v43, 16, v58
	v_and_or_b32 v43, v19, s29, v43
	v_and_or_b32 v42, v42, s29, v57
	v_and_or_b32 v41, v41, s29, v56
	v_and_or_b32 v40, v40, s29, v59
	ds_read2_b64 v[56:59], v69 offset0:128 offset1:132
	s_waitcnt lgkmcnt(1)
	v_mfma_f32_16x16x32_bf16 v[36:39], v[36:39], v[40:43], v[44:47]
	s_nop 2
	ds_read2_b64 v[44:47], v18 offset0:64 offset1:68
	s_waitcnt lgkmcnt(0)
	v_mfma_f32_16x16x32_bf16 v[44:47], v[44:47], v[40:43], v[52:55]
	s_nop 2
	ds_read2_b64 v[52:55], v68 offset0:96 offset1:100
	s_waitcnt lgkmcnt(0)
	v_mfma_f32_16x16x32_bf16 v[52:55], v[52:55], v[40:43], v[60:63]
	v_mfma_f32_16x16x32_bf16 v[40:43], v[56:59], v[40:43], v[48:51]
	v_mul_f32_e64 v32, v32, v10
	v_mul_f32_e64 v33, v33, v10
	v_pk_mul_f32 v[34:35], v[34:35], v[10:11] op_sel_hi:[1,0]
	v_pk_mul_f32 v[28:29], v[28:29], v[10:11] op_sel_hi:[1,0]
	v_pk_mul_f32 v[30:31], v[30:31], v[10:11] op_sel_hi:[1,0]
	v_bfe_u32 v19, v35, 16, 1
	v_bfe_u32 v48, v34, 16, 1
	v_bfe_u32 v49, v33, 16, 1
	v_bfe_u32 v50, v32, 16, 1
	v_add3_u32 v32, v32, v50, s33
	v_add3_u32 v33, v33, v49, s33
	v_add3_u32 v34, v34, v48, s33
	v_add3_u32 v19, v35, v19, s33
	v_bfe_u32 v35, v28, 16, 1
	v_bfe_u32 v48, v29, 16, 1
	v_bfe_u32 v49, v30, 16, 1
	v_bfe_u32 v50, v31, 16, 1
	v_add3_u32 v50, v31, v50, s33
	v_add3_u32 v49, v30, v49, s33
	v_add3_u32 v48, v29, v48, s33
	v_add3_u32 v35, v28, v35, s33
	ds_read2_b64 v[28:31], v11 offset0:40 offset1:44
	v_lshrrev_b32_e32 v51, 16, v35
	v_lshrrev_b32_e32 v48, 16, v48
	v_lshrrev_b32_e32 v49, 16, v49
	v_lshrrev_b32_e32 v35, 16, v50
	v_and_or_b32 v35, v19, s29, v35
	v_and_or_b32 v34, v34, s29, v49
	v_and_or_b32 v33, v33, s29, v48
	v_and_or_b32 v32, v32, s29, v51
	ds_read2_b64 v[48:51], v69 offset0:136 offset1:140
	s_waitcnt lgkmcnt(1)
	v_mfma_f32_16x16x32_bf16 v[28:31], v[28:31], v[32:35], v[36:39]
	s_nop 2
	ds_read2_b64 v[36:39], v18 offset0:72 offset1:76
	s_waitcnt lgkmcnt(0)
	v_mfma_f32_16x16x32_bf16 v[36:39], v[36:39], v[32:35], v[44:47]
	s_nop 2
	ds_read2_b64 v[44:47], v68 offset0:104 offset1:108
	s_waitcnt lgkmcnt(0)
	v_mfma_f32_16x16x32_bf16 v[44:47], v[44:47], v[32:35], v[52:55]
	v_mfma_f32_16x16x32_bf16 v[32:35], v[48:51], v[32:35], v[40:43]
	v_mul_f32_e64 v24, v24, v10
	v_mul_f32_e64 v25, v25, v10
	v_pk_mul_f32 v[26:27], v[26:27], v[10:11] op_sel_hi:[1,0]
	v_pk_mul_f32 v[20:21], v[20:21], v[10:11] op_sel_hi:[1,0]
	v_pk_mul_f32 v[22:23], v[22:23], v[10:11] op_sel_hi:[1,0]
	v_bfe_u32 v19, v27, 16, 1
	v_bfe_u32 v40, v26, 16, 1
	v_bfe_u32 v41, v25, 16, 1
	v_bfe_u32 v42, v24, 16, 1
	v_add3_u32 v24, v24, v42, s33
	v_add3_u32 v25, v25, v41, s33
	v_add3_u32 v26, v26, v40, s33
	v_add3_u32 v19, v27, v19, s33
	v_bfe_u32 v27, v20, 16, 1
	v_bfe_u32 v40, v21, 16, 1
	v_bfe_u32 v41, v22, 16, 1
	v_bfe_u32 v42, v23, 16, 1
	v_add3_u32 v42, v23, v42, s33
	v_add3_u32 v41, v22, v41, s33
	v_add3_u32 v40, v21, v40, s33
	v_add3_u32 v27, v20, v27, s33
	ds_read2_b64 v[20:23], v11 offset0:48 offset1:52
	v_lshrrev_b32_e32 v43, 16, v27
	v_lshrrev_b32_e32 v40, 16, v40
	v_lshrrev_b32_e32 v41, 16, v41
	v_lshrrev_b32_e32 v27, 16, v42
	v_and_or_b32 v27, v19, s29, v27
	v_and_or_b32 v26, v26, s29, v41
	v_and_or_b32 v25, v25, s29, v40
	v_and_or_b32 v24, v24, s29, v43
	ds_read2_b64 v[40:43], v69 offset0:144 offset1:148
	s_waitcnt lgkmcnt(1)
	v_mfma_f32_16x16x32_bf16 v[20:23], v[20:23], v[24:27], v[28:31]
	s_nop 2
	ds_read2_b64 v[28:31], v18 offset0:80 offset1:84
	s_waitcnt lgkmcnt(0)
	v_mfma_f32_16x16x32_bf16 v[28:31], v[28:31], v[24:27], v[36:39]
	s_nop 2
	ds_read2_b64 v[36:39], v68 offset0:112 offset1:116
	s_waitcnt lgkmcnt(0)
	v_mfma_f32_16x16x32_bf16 v[36:39], v[36:39], v[24:27], v[44:47]
	v_mfma_f32_16x16x32_bf16 v[24:27], v[40:43], v[24:27], v[32:35]
	v_mul_f32_e64 v16, v16, v10
	v_mul_f32_e64 v17, v17, v10
	v_pk_mul_f32 v[14:15], v[14:15], v[10:11] op_sel_hi:[1,0]
	v_pk_mul_f32 v[12:13], v[12:13], v[10:11] op_sel_hi:[1,0]
	v_pk_mul_f32 v[8:9], v[8:9], v[10:11] op_sel_hi:[1,0]
	v_bfe_u32 v10, v15, 16, 1
	v_bfe_u32 v32, v17, 16, 1
	v_bfe_u32 v33, v16, 16, 1
	v_add3_u32 v16, v16, v33, s33
	v_add3_u32 v17, v17, v32, s33
	v_add3_u32 v15, v15, v10, s33
	v_bfe_u32 v10, v12, 16, 1
	v_bfe_u32 v32, v8, 16, 1
	v_bfe_u32 v33, v9, 16, 1
	v_add3_u32 v33, v9, v33, s33
	v_add3_u32 v32, v8, v32, s33
	v_add3_u32 v12, v12, v10, s33
	ds_read2_b64 v[8:11], v11 offset0:56 offset1:60
	v_bfe_u32 v19, v14, 16, 1
	v_add3_u32 v14, v14, v19, s33
	v_bfe_u32 v19, v13, 16, 1
	v_add3_u32 v13, v13, v19, s33
	v_lshrrev_b32_e32 v12, 16, v12
	v_lshrrev_b32_e32 v13, 16, v13
	v_lshrrev_b32_e32 v19, 16, v32
	v_lshrrev_b32_e32 v32, 16, v33
	v_and_or_b32 v35, v15, s29, v32
	v_and_or_b32 v34, v14, s29, v19
	v_and_or_b32 v33, v17, s29, v13
	v_and_or_b32 v32, v16, s29, v12
	s_waitcnt lgkmcnt(0)
	s_nop 0
	v_mfma_f32_16x16x32_bf16 v[20:23], v[8:11], v[32:35], v[20:23]
	ds_read2_b64 v[8:11], v18 offset0:88 offset1:92
	s_waitcnt lgkmcnt(0)
	v_mfma_f32_16x16x32_bf16 v[16:19], v[8:11], v[32:35], v[28:31]
	ds_read2_b64 v[8:11], v68 offset0:120 offset1:124
	s_waitcnt lgkmcnt(0)
	v_mfma_f32_16x16x32_bf16 v[12:15], v[8:11], v[32:35], v[36:39]
	ds_read2_b64 v[8:11], v69 offset0:152 offset1:156
	s_waitcnt lgkmcnt(0)
	v_mfma_f32_16x16x32_bf16 v[8:11], v[8:11], v[32:35], v[24:27]
	s_and_saveexec_b64 s[2:3], s[0:1]
	s_cbranch_execz .LBB0_253
	s_nop 0
	v_bfe_u32 v26, v20, 16, 1
	v_add3_u32 v20, v20, v26, s33
	v_bfe_u32 v26, v21, 16, 1
	v_add3_u32 v21, v21, v26, s33
	v_lshrrev_b32_e32 v20, 16, v20
	v_add_u32_e32 v24, s6, v81
	v_and_or_b32 v20, v21, s29, v20
	v_bfe_u32 v21, v22, 16, 1
	v_ashrrev_i32_e32 v25, 31, v24
	v_add3_u32 v21, v22, v21, s33
	v_bfe_u32 v22, v23, 16, 1
	v_lshlrev_b64 v[24:25], 11, v[24:25]
	v_add3_u32 v22, v23, v22, s33
	v_lshrrev_b32_e32 v21, 16, v21
	v_lshl_add_u64 v[24:25], v[76:77], 0, v[24:25]
	v_and_or_b32 v21, v22, s29, v21
	global_store_dwordx2 v[24:25], v[20:21], off offset:1536
	v_bfe_u32 v20, v16, 16, 1
	v_add3_u32 v16, v16, v20, s33
	v_bfe_u32 v20, v17, 16, 1
	v_add3_u32 v17, v17, v20, s33
	v_lshrrev_b32_e32 v16, 16, v16
	v_and_or_b32 v16, v17, s29, v16
	v_bfe_u32 v17, v18, 16, 1
	v_add3_u32 v17, v18, v17, s33
	v_bfe_u32 v18, v19, 16, 1
	v_add3_u32 v18, v19, v18, s33
	v_lshrrev_b32_e32 v17, 16, v17
	v_and_or_b32 v17, v18, s29, v17
	global_store_dwordx2 v[24:25], v[16:17], off offset:1568
	v_bfe_u32 v16, v12, 16, 1
	v_add3_u32 v12, v12, v16, s33
	v_bfe_u32 v16, v13, 16, 1
	v_add3_u32 v13, v13, v16, s33
	v_lshrrev_b32_e32 v12, 16, v12
	v_and_or_b32 v12, v13, s29, v12
	v_bfe_u32 v13, v14, 16, 1
	v_add3_u32 v13, v14, v13, s33
	v_bfe_u32 v14, v15, 16, 1
	v_add3_u32 v14, v15, v14, s33
	v_lshrrev_b32_e32 v13, 16, v13
	v_and_or_b32 v13, v14, s29, v13
	global_store_dwordx2 v[24:25], v[12:13], off offset:1600
	v_bfe_u32 v12, v8, 16, 1
	v_add3_u32 v8, v8, v12, s33
	v_bfe_u32 v12, v9, 16, 1
	v_add3_u32 v9, v9, v12, s33
	v_lshrrev_b32_e32 v8, 16, v8
	v_and_or_b32 v8, v9, s29, v8
	v_bfe_u32 v9, v10, 16, 1
	v_add3_u32 v9, v10, v9, s33
	v_bfe_u32 v10, v11, 16, 1
	v_add3_u32 v10, v11, v10, s33
	v_lshrrev_b32_e32 v9, 16, v9
	v_and_or_b32 v9, v10, s29, v9
	global_store_dwordx2 v[24:25], v[8:9], off offset:1632
	s_branch .LBB0_253

.LBB0_314:
	ds_read_b128 v[116:119], v66
	ds_read_b128 v[120:123], v66 offset:64
	ds_read_b128 v[124:127], v66 offset:2304
	ds_read_b128 v[128:131], v66 offset:2368
	ds_read_b128 v[132:135], v66 offset:4608
	ds_read_b128 v[136:139], v66 offset:4672
	ds_read_b128 v[140:143], v66 offset:6912
	ds_read_b128 v[144:147], v66 offset:6976
	ds_read_b128 v[148:151], v66 offset:9216
	ds_read_b128 v[152:155], v66 offset:9280
	ds_read_b128 v[156:159], v66 offset:11520
	ds_read_b128 v[160:163], v66 offset:11584
	s_waitcnt lgkmcnt(6)
	v_mfma_f32_16x16x32_bf16 v[8:11], v[116:119], v[32:35], 0
	v_mfma_f32_16x16x32_bf16 v[12:15], v[124:127], v[32:35], 0
	v_mfma_f32_16x16x32_bf16 v[20:23], v[132:135], v[32:35], 0
	v_mfma_f32_16x16x32_bf16 v[8:11], v[120:123], v[16:19], v[8:11]
	v_mfma_f32_16x16x32_bf16 v[12:15], v[128:131], v[16:19], v[12:15]
	v_mfma_f32_16x16x32_bf16 v[20:23], v[136:139], v[16:19], v[20:23]
	ds_read_b128 v[116:119], v66 offset:13824
	ds_read_b128 v[120:123], v66 offset:13888
	ds_read_b128 v[124:127], v66 offset:16128
	ds_read_b128 v[128:131], v66 offset:16192
	ds_read_b128 v[132:135], v66 offset:18432
	ds_read_b128 v[136:139], v66 offset:18496
	s_waitcnt lgkmcnt(6)
	v_mfma_f32_16x16x32_bf16 v[24:27], v[140:143], v[32:35], 0
	v_mfma_f32_16x16x32_bf16 v[28:31], v[148:151], v[32:35], 0
	v_mfma_f32_16x16x32_bf16 v[36:39], v[156:159], v[32:35], 0
	v_mfma_f32_16x16x32_bf16 v[24:27], v[144:147], v[16:19], v[24:27]
	v_mfma_f32_16x16x32_bf16 v[28:31], v[152:155], v[16:19], v[28:31]
	v_mfma_f32_16x16x32_bf16 v[36:39], v[160:163], v[16:19], v[36:39]
	ds_read_b128 v[140:143], v66 offset:20736
	ds_read_b128 v[144:147], v66 offset:20800
	ds_read_b128 v[148:151], v66 offset:23040
	ds_read_b128 v[152:155], v66 offset:23104
	s_waitcnt lgkmcnt(4)
	v_mfma_f32_16x16x32_bf16 v[40:43], v[116:119], v[32:35], 0
	v_mfma_f32_16x16x32_bf16 v[44:47], v[124:127], v[32:35], 0
	v_mfma_f32_16x16x32_bf16 v[48:51], v[132:135], v[32:35], 0
	v_mfma_f32_16x16x32_bf16 v[40:43], v[120:123], v[16:19], v[40:43]
	v_mfma_f32_16x16x32_bf16 v[44:47], v[128:131], v[16:19], v[44:47]
	v_mfma_f32_16x16x32_bf16 v[48:51], v[136:139], v[16:19], v[48:51]
	s_waitcnt lgkmcnt(0)
	v_mfma_f32_16x16x32_bf16 v[52:55], v[140:143], v[32:35], 0
	v_mfma_f32_16x16x32_bf16 v[56:59], v[148:151], v[32:35], 0
	v_mfma_f32_16x16x32_bf16 v[52:55], v[144:147], v[16:19], v[52:55]
	v_mfma_f32_16x16x32_bf16 v[56:59], v[152:155], v[16:19], v[56:59]
	ds_read_b128 v[116:119], v66 offset:25344
	ds_read_b128 v[120:123], v66 offset:25408
	s_waitcnt lgkmcnt(0)
	v_mfma_f32_16x16x32_bf16 v[124:127], v[116:119], v[32:35], 0
	v_mfma_f32_16x16x32_bf16 v[16:19], v[120:123], v[16:19], v[124:127]
	s_cmp_lt_i32 s6, 1
	v_mov_b32_e32 v68, v72
	s_cbranch_scc1 .LBB0_319
	s_cmp_lg_u32 s6, 1
	s_mov_b64 vcc, -1
	s_cbranch_scc0 .LBB0_317
	s_mov_b64 vcc, 0
